# mixer instruction diet: exact fused mul+add pairs and packed constant ops in GN/pooling (-73 VALU per 16-token run), on v28
# speedup vs baseline: 1.0049x; 1.0049x over previous
; __device__ __forceinline__ unsigned pk2(float lo, float hi) { f32x2v v = {lo, hi}; b16x2v b = __builtin_convertvector(v, b16x2v); return __builtin_bit_cast(unsigned, b); }
; __device__ __forceinline__ f32x2v bf2(unsigned v) { return (f32x2v){bflo(v), bfhi(v)}; }
; template <int W>
; __device__ __forceinline__ void pool_prompt_w(const unsigned (&pin)[31], int t0, unsigned* dst  ) {
;     f32x2v s = {0.f, 0.f};
; #pragma unroll
;     for (int i = 0; i < W; ++i) s = s + bf2(pin[15 - i]);
; #pragma unroll
;     for (int t = 0; t < 16; ++t) {
;         if (t > 0) s = s + (bf2(pin[15 + t]) - bf2(pin[15 + t - W]));
;         const float cnt = (float)min(t0 + t + 1, W); const f32x2v cur = bf2(pin[15 + t]);
;         dst[(size_t)t * 512] = pk2(s.x / cnt - cur.x, s.y / cnt - cur.y);
;     }
; }
; __device__ __forceinline__ void mixer_prompt_run(const Args& p, int run, int c2) {
;     ...
;         if (gi == 0) pool_prompt_w<2>(pin, t0, dst); else if (gi == 1) pool_prompt_w<4>(pin, t0, dst); else if (gi == 2) pool_prompt_w<8>(pin, t0, dst); else pool_prompt_w<16>(pin, t0, dst);
.Lmx_pool0:
	v_lshlrev_b32_e32 v172, 16, v223
	v_and_b32_e32 v173, 0xffff0000, v223
	v_lshlrev_b32_e32 v176, 16, v222
	v_and_b32_e32 v177, 0xffff0000, v222
	v_pk_add_f32 v[172:173], v[172:173], v[176:177]
	v_lshlrev_b32_e32 v174, 16, v223
	v_and_b32_e32 v175, 0xffff0000, v223
	s_cmp_eq_u32 s64, 0
	s_cbranch_scc1 .Lmx_ps0_0
	v_pk_fma_f32 v[182:183], v[172:173], s[72:73], v[174:175] neg_lo:[0,0,1] neg_hi:[0,0,1]
.Lmx_pb0_0:
	v_cvt_pk_bf16_f32 v184, v182, v183
	global_store_dword v105, v184, s[76:77] offset:-3072
	v_lshlrev_b32_e32 v174, 16, v224
	v_and_b32_e32 v175, 0xffff0000, v224
	v_lshlrev_b32_e32 v176, 16, v222
	v_and_b32_e32 v177, 0xffff0000, v222
	v_pk_add_f32 v[178:179], v[174:175], v[176:177] neg_lo:[0,1] neg_hi:[0,1]
	v_pk_add_f32 v[172:173], v[172:173], v[178:179]
	v_pk_fma_f32 v[182:183], v[172:173], s[72:73], v[174:175] neg_lo:[0,0,1] neg_hi:[0,0,1]
	v_cvt_pk_bf16_f32 v185, v182, v183
	global_store_dword v105, v185, s[76:77] offset:-1024
	v_lshlrev_b32_e32 v174, 16, v225
	v_and_b32_e32 v175, 0xffff0000, v225
	v_lshlrev_b32_e32 v176, 16, v223
	v_and_b32_e32 v177, 0xffff0000, v223
	v_pk_add_f32 v[178:179], v[174:175], v[176:177] neg_lo:[0,1] neg_hi:[0,1]
	v_pk_add_f32 v[172:173], v[172:173], v[178:179]
	v_pk_fma_f32 v[182:183], v[172:173], s[72:73], v[174:175] neg_lo:[0,0,1] neg_hi:[0,0,1]
	v_cvt_pk_bf16_f32 v186, v182, v183
	global_store_dword v105, v186, s[76:77] offset:1024
	v_lshlrev_b32_e32 v174, 16, v226
	v_and_b32_e32 v175, 0xffff0000, v226
	v_lshlrev_b32_e32 v176, 16, v224
	v_and_b32_e32 v177, 0xffff0000, v224
	v_pk_add_f32 v[178:179], v[174:175], v[176:177] neg_lo:[0,1] neg_hi:[0,1]
	v_pk_add_f32 v[172:173], v[172:173], v[178:179]
	v_pk_fma_f32 v[182:183], v[172:173], s[72:73], v[174:175] neg_lo:[0,0,1] neg_hi:[0,0,1]
	v_cvt_pk_bf16_f32 v187, v182, v183
	global_store_dword v105, v187, s[76:77] offset:3072
	v_lshlrev_b32_e32 v174, 16, v227
	v_and_b32_e32 v175, 0xffff0000, v227
	v_lshlrev_b32_e32 v176, 16, v225
	v_and_b32_e32 v177, 0xffff0000, v225
	v_pk_add_f32 v[178:179], v[174:175], v[176:177] neg_lo:[0,1] neg_hi:[0,1]
	v_pk_add_f32 v[172:173], v[172:173], v[178:179]
	v_pk_fma_f32 v[182:183], v[172:173], s[72:73], v[174:175] neg_lo:[0,0,1] neg_hi:[0,0,1]
	v_cvt_pk_bf16_f32 v184, v182, v183
	s_add_u32 s76, s76, 0x2000
	s_addc_u32 s77, s77, 0
	global_store_dword v105, v184, s[76:77] offset:-3072
	v_lshlrev_b32_e32 v174, 16, v228
	v_and_b32_e32 v175, 0xffff0000, v228
	v_lshlrev_b32_e32 v176, 16, v226
	v_and_b32_e32 v177, 0xffff0000, v226
	v_pk_add_f32 v[178:179], v[174:175], v[176:177] neg_lo:[0,1] neg_hi:[0,1]
	v_pk_add_f32 v[172:173], v[172:173], v[178:179]
	v_pk_fma_f32 v[182:183], v[172:173], s[72:73], v[174:175] neg_lo:[0,0,1] neg_hi:[0,0,1]
	v_cvt_pk_bf16_f32 v185, v182, v183
	global_store_dword v105, v185, s[76:77] offset:-1024
	v_lshlrev_b32_e32 v174, 16, v229
	v_and_b32_e32 v175, 0xffff0000, v229
	v_lshlrev_b32_e32 v176, 16, v227
	v_and_b32_e32 v177, 0xffff0000, v227
	v_pk_add_f32 v[178:179], v[174:175], v[176:177] neg_lo:[0,1] neg_hi:[0,1]
	v_pk_add_f32 v[172:173], v[172:173], v[178:179]
	v_pk_fma_f32 v[182:183], v[172:173], s[72:73], v[174:175] neg_lo:[0,0,1] neg_hi:[0,0,1]
	v_cvt_pk_bf16_f32 v186, v182, v183
	global_store_dword v105, v186, s[76:77] offset:1024
	v_lshlrev_b32_e32 v174, 16, v230
	v_and_b32_e32 v175, 0xffff0000, v230
	v_lshlrev_b32_e32 v176, 16, v228
	v_and_b32_e32 v177, 0xffff0000, v228
	v_pk_add_f32 v[178:179], v[174:175], v[176:177] neg_lo:[0,1] neg_hi:[0,1]
	v_pk_add_f32 v[172:173], v[172:173], v[178:179]
	v_pk_fma_f32 v[182:183], v[172:173], s[72:73], v[174:175] neg_lo:[0,0,1] neg_hi:[0,0,1]
	v_cvt_pk_bf16_f32 v187, v182, v183
	global_store_dword v105, v187, s[76:77] offset:3072
	v_lshlrev_b32_e32 v174, 16, v231
	v_and_b32_e32 v175, 0xffff0000, v231
	v_lshlrev_b32_e32 v176, 16, v229
	v_and_b32_e32 v177, 0xffff0000, v229
	v_pk_add_f32 v[178:179], v[174:175], v[176:177] neg_lo:[0,1] neg_hi:[0,1]
	v_pk_add_f32 v[172:173], v[172:173], v[178:179]
	v_pk_fma_f32 v[182:183], v[172:173], s[72:73], v[174:175] neg_lo:[0,0,1] neg_hi:[0,0,1]
	v_cvt_pk_bf16_f32 v184, v182, v183
	s_add_u32 s76, s76, 0x2000
	s_addc_u32 s77, s77, 0
	s_waitcnt vmcnt(40)
	global_store_dword v105, v184, s[76:77] offset:-3072
	v_lshlrev_b32_e32 v174, 16, v232
	v_and_b32_e32 v175, 0xffff0000, v232
	v_lshlrev_b32_e32 v176, 16, v230
	v_and_b32_e32 v177, 0xffff0000, v230
	v_pk_add_f32 v[178:179], v[174:175], v[176:177] neg_lo:[0,1] neg_hi:[0,1]
	v_pk_add_f32 v[172:173], v[172:173], v[178:179]
	v_pk_fma_f32 v[182:183], v[172:173], s[72:73], v[174:175] neg_lo:[0,0,1] neg_hi:[0,0,1]
	v_cvt_pk_bf16_f32 v185, v182, v183
	global_store_dword v105, v185, s[76:77] offset:-1024
	v_lshlrev_b32_e32 v174, 16, v233
	v_and_b32_e32 v175, 0xffff0000, v233
	v_lshlrev_b32_e32 v176, 16, v231
	v_and_b32_e32 v177, 0xffff0000, v231
	v_pk_add_f32 v[178:179], v[174:175], v[176:177] neg_lo:[0,1] neg_hi:[0,1]
	v_pk_add_f32 v[172:173], v[172:173], v[178:179]
	v_pk_fma_f32 v[182:183], v[172:173], s[72:73], v[174:175] neg_lo:[0,0,1] neg_hi:[0,0,1]
	v_cvt_pk_bf16_f32 v186, v182, v183
	global_store_dword v105, v186, s[76:77] offset:1024
	v_lshlrev_b32_e32 v174, 16, v234
	v_and_b32_e32 v175, 0xffff0000, v234
	v_lshlrev_b32_e32 v176, 16, v232
	v_and_b32_e32 v177, 0xffff0000, v232
	v_pk_add_f32 v[178:179], v[174:175], v[176:177] neg_lo:[0,1] neg_hi:[0,1]
	v_pk_add_f32 v[172:173], v[172:173], v[178:179]
	v_pk_fma_f32 v[182:183], v[172:173], s[72:73], v[174:175] neg_lo:[0,0,1] neg_hi:[0,0,1]
	v_cvt_pk_bf16_f32 v187, v182, v183
	global_store_dword v105, v187, s[76:77] offset:3072
	v_lshlrev_b32_e32 v174, 16, v235
	v_and_b32_e32 v175, 0xffff0000, v235
; __device__ __forceinline__ unsigned pk2(float lo, float hi) { f32x2v v = {lo, hi}; b16x2v b = __builtin_convertvector(v, b16x2v); return __builtin_bit_cast(unsigned, b); }
; __device__ __forceinline__ f32x2v bf2(unsigned v) { return (f32x2v){bflo(v), bfhi(v)}; }
; template <int W>
; __device__ __forceinline__ void pool_prompt_w(const unsigned (&pin)[31], int t0, unsigned* dst  ) {
;     f32x2v s = {0.f, 0.f};
; #pragma unroll
;     for (int i = 0; i < W; ++i) s = s + bf2(pin[15 - i]);
; #pragma unroll
;     for (int t = 0; t < 16; ++t) {
;         if (t > 0) s = s + (bf2(pin[15 + t]) - bf2(pin[15 + t - W]));
;         const float cnt = (float)min(t0 + t + 1, W); const f32x2v cur = bf2(pin[15 + t]);
;         dst[(size_t)t * 512] = pk2(s.x / cnt - cur.x, s.y / cnt - cur.y);
;     }
; }
; __device__ __forceinline__ void mixer_prompt_run(const Args& p, int run, int c2) {
;     ...
;         if (gi == 0) pool_prompt_w<2>(pin, t0, dst); else if (gi == 1) pool_prompt_w<4>(pin, t0, dst); else if (gi == 2) pool_prompt_w<8>(pin, t0, dst); else pool_prompt_w<16>(pin, t0, dst);
	v_lshlrev_b32_e32 v176, 16, v233
	v_and_b32_e32 v177, 0xffff0000, v233
	v_pk_add_f32 v[178:179], v[174:175], v[176:177] neg_lo:[0,1] neg_hi:[0,1]
	v_pk_add_f32 v[172:173], v[172:173], v[178:179]
	v_pk_fma_f32 v[182:183], v[172:173], s[72:73], v[174:175] neg_lo:[0,0,1] neg_hi:[0,0,1]
	v_cvt_pk_bf16_f32 v184, v182, v183
	s_add_u32 s76, s76, 0x2000
	s_addc_u32 s77, s77, 0
	global_store_dword v105, v184, s[76:77] offset:-3072
	v_lshlrev_b32_e32 v174, 16, v236
	v_and_b32_e32 v175, 0xffff0000, v236
	v_lshlrev_b32_e32 v176, 16, v234
	v_and_b32_e32 v177, 0xffff0000, v234
	v_pk_add_f32 v[178:179], v[174:175], v[176:177] neg_lo:[0,1] neg_hi:[0,1]
	v_pk_add_f32 v[172:173], v[172:173], v[178:179]
	v_pk_fma_f32 v[182:183], v[172:173], s[72:73], v[174:175] neg_lo:[0,0,1] neg_hi:[0,0,1]
	v_cvt_pk_bf16_f32 v185, v182, v183
	global_store_dword v105, v185, s[76:77] offset:-1024
	v_lshlrev_b32_e32 v174, 16, v237
	v_and_b32_e32 v175, 0xffff0000, v237
	v_lshlrev_b32_e32 v176, 16, v235
	v_and_b32_e32 v177, 0xffff0000, v235
	v_pk_add_f32 v[178:179], v[174:175], v[176:177] neg_lo:[0,1] neg_hi:[0,1]
	v_pk_add_f32 v[172:173], v[172:173], v[178:179]
	v_pk_fma_f32 v[182:183], v[172:173], s[72:73], v[174:175] neg_lo:[0,0,1] neg_hi:[0,0,1]
	v_cvt_pk_bf16_f32 v186, v182, v183
	global_store_dword v105, v186, s[76:77] offset:1024
	v_lshlrev_b32_e32 v174, 16, v238
	v_and_b32_e32 v175, 0xffff0000, v238
	v_lshlrev_b32_e32 v176, 16, v236
	v_and_b32_e32 v177, 0xffff0000, v236
	v_pk_add_f32 v[178:179], v[174:175], v[176:177] neg_lo:[0,1] neg_hi:[0,1]
	v_pk_add_f32 v[172:173], v[172:173], v[178:179]
	v_pk_fma_f32 v[182:183], v[172:173], s[72:73], v[174:175] neg_lo:[0,0,1] neg_hi:[0,0,1]
	v_cvt_pk_bf16_f32 v187, v182, v183
	global_store_dword v105, v187, s[76:77] offset:3072
	s_branch .Lmx_pool_done
.Lmx_ps0_0:
	s_mov_b32 s78, 0x3f800000
	s_mov_b32 s79, 0x3f800000
	v_mul_f32_e32 v180, s79, v172
	v_fma_f32 v240, -v180, s78, v172
	v_fma_f32 v180, v240, s79, v180
	v_mul_f32_e32 v181, s79, v173
	v_fma_f32 v240, -v181, s78, v173
	v_fma_f32 v181, v240, s79, v181
	v_pk_add_f32 v[182:183], v[180:181], v[174:175] neg_lo:[0,1] neg_hi:[0,1]
	s_branch .Lmx_pb0_0
.Lmx_pool1:
	v_lshlrev_b32_e32 v172, 16, v223
	v_and_b32_e32 v173, 0xffff0000, v223
	v_lshlrev_b32_e32 v176, 16, v222
	v_and_b32_e32 v177, 0xffff0000, v222
	v_pk_add_f32 v[172:173], v[172:173], v[176:177]
	v_lshlrev_b32_e32 v176, 16, v221
	v_and_b32_e32 v177, 0xffff0000, v221
	v_pk_add_f32 v[172:173], v[172:173], v[176:177]
	v_lshlrev_b32_e32 v176, 16, v220
	v_and_b32_e32 v177, 0xffff0000, v220
	v_pk_add_f32 v[172:173], v[172:173], v[176:177]
	v_lshlrev_b32_e32 v174, 16, v223
	v_and_b32_e32 v175, 0xffff0000, v223
	s_cmp_eq_u32 s64, 0
	s_cbranch_scc1 .Lmx_ps1_0
	v_pk_fma_f32 v[182:183], v[172:173], s[72:73], v[174:175] neg_lo:[0,0,1] neg_hi:[0,0,1]
.Lmx_pb1_0:
	v_cvt_pk_bf16_f32 v184, v182, v183
	global_store_dword v105, v184, s[76:77] offset:-3072
	v_lshlrev_b32_e32 v174, 16, v224
	v_and_b32_e32 v175, 0xffff0000, v224
	v_lshlrev_b32_e32 v176, 16, v220
	v_and_b32_e32 v177, 0xffff0000, v220
	v_pk_add_f32 v[178:179], v[174:175], v[176:177] neg_lo:[0,1] neg_hi:[0,1]
	v_pk_add_f32 v[172:173], v[172:173], v[178:179]
	s_cmp_eq_u32 s64, 0
	s_cbranch_scc1 .Lmx_ps1_1
	v_pk_fma_f32 v[182:183], v[172:173], s[72:73], v[174:175] neg_lo:[0,0,1] neg_hi:[0,0,1]
.Lmx_pb1_1:
	v_cvt_pk_bf16_f32 v185, v182, v183
	global_store_dword v105, v185, s[76:77] offset:-1024
	v_lshlrev_b32_e32 v174, 16, v225
	v_and_b32_e32 v175, 0xffff0000, v225
	v_lshlrev_b32_e32 v176, 16, v221
	v_and_b32_e32 v177, 0xffff0000, v221
	v_pk_add_f32 v[178:179], v[174:175], v[176:177] neg_lo:[0,1] neg_hi:[0,1]
	v_pk_add_f32 v[172:173], v[172:173], v[178:179]
	s_cmp_eq_u32 s64, 0
	s_cbranch_scc1 .Lmx_ps1_2
	v_pk_fma_f32 v[182:183], v[172:173], s[72:73], v[174:175] neg_lo:[0,0,1] neg_hi:[0,0,1]
; __device__ __forceinline__ unsigned pk2(float lo, float hi) { f32x2v v = {lo, hi}; b16x2v b = __builtin_convertvector(v, b16x2v); return __builtin_bit_cast(unsigned, b); }
; __device__ __forceinline__ f32x2v bf2(unsigned v) { return (f32x2v){bflo(v), bfhi(v)}; }
; template <int W>
; __device__ __forceinline__ void pool_prompt_w(const unsigned (&pin)[31], int t0, unsigned* dst  ) {
;     f32x2v s = {0.f, 0.f};
; #pragma unroll
;     for (int i = 0; i < W; ++i) s = s + bf2(pin[15 - i]);
; #pragma unroll
;     for (int t = 0; t < 16; ++t) {
;         if (t > 0) s = s + (bf2(pin[15 + t]) - bf2(pin[15 + t - W]));
;         const float cnt = (float)min(t0 + t + 1, W); const f32x2v cur = bf2(pin[15 + t]);
;         dst[(size_t)t * 512] = pk2(s.x / cnt - cur.x, s.y / cnt - cur.y);
;     }
; }
; __device__ __forceinline__ void mixer_prompt_run(const Args& p, int run, int c2) {
;     ...
;         if (gi == 0) pool_prompt_w<2>(pin, t0, dst); else if (gi == 1) pool_prompt_w<4>(pin, t0, dst); else if (gi == 2) pool_prompt_w<8>(pin, t0, dst); else pool_prompt_w<16>(pin, t0, dst);
.Lmx_pb1_2:
	v_cvt_pk_bf16_f32 v186, v182, v183
	global_store_dword v105, v186, s[76:77] offset:1024
	v_lshlrev_b32_e32 v174, 16, v226
	v_and_b32_e32 v175, 0xffff0000, v226
	v_lshlrev_b32_e32 v176, 16, v222
	v_and_b32_e32 v177, 0xffff0000, v222
	v_pk_add_f32 v[178:179], v[174:175], v[176:177] neg_lo:[0,1] neg_hi:[0,1]
	v_pk_add_f32 v[172:173], v[172:173], v[178:179]
	v_pk_fma_f32 v[182:183], v[172:173], s[72:73], v[174:175] neg_lo:[0,0,1] neg_hi:[0,0,1]
	v_cvt_pk_bf16_f32 v187, v182, v183
	global_store_dword v105, v187, s[76:77] offset:3072
	v_lshlrev_b32_e32 v174, 16, v227
	v_and_b32_e32 v175, 0xffff0000, v227
	v_lshlrev_b32_e32 v176, 16, v223
	v_and_b32_e32 v177, 0xffff0000, v223
	v_pk_add_f32 v[178:179], v[174:175], v[176:177] neg_lo:[0,1] neg_hi:[0,1]
	v_pk_add_f32 v[172:173], v[172:173], v[178:179]
	v_pk_fma_f32 v[182:183], v[172:173], s[72:73], v[174:175] neg_lo:[0,0,1] neg_hi:[0,0,1]
	v_cvt_pk_bf16_f32 v184, v182, v183
	s_add_u32 s76, s76, 0x2000
	s_addc_u32 s77, s77, 0
	global_store_dword v105, v184, s[76:77] offset:-3072
	v_lshlrev_b32_e32 v174, 16, v228
	v_and_b32_e32 v175, 0xffff0000, v228
	v_lshlrev_b32_e32 v176, 16, v224
	v_and_b32_e32 v177, 0xffff0000, v224
	v_pk_add_f32 v[178:179], v[174:175], v[176:177] neg_lo:[0,1] neg_hi:[0,1]
	v_pk_add_f32 v[172:173], v[172:173], v[178:179]
	v_pk_fma_f32 v[182:183], v[172:173], s[72:73], v[174:175] neg_lo:[0,0,1] neg_hi:[0,0,1]
	v_cvt_pk_bf16_f32 v185, v182, v183
	global_store_dword v105, v185, s[76:77] offset:-1024
	v_lshlrev_b32_e32 v174, 16, v229
	v_and_b32_e32 v175, 0xffff0000, v229
	v_lshlrev_b32_e32 v176, 16, v225
	v_and_b32_e32 v177, 0xffff0000, v225
	v_pk_add_f32 v[178:179], v[174:175], v[176:177] neg_lo:[0,1] neg_hi:[0,1]
	v_pk_add_f32 v[172:173], v[172:173], v[178:179]
	v_pk_fma_f32 v[182:183], v[172:173], s[72:73], v[174:175] neg_lo:[0,0,1] neg_hi:[0,0,1]
	v_cvt_pk_bf16_f32 v186, v182, v183
	global_store_dword v105, v186, s[76:77] offset:1024
	v_lshlrev_b32_e32 v174, 16, v230
	v_and_b32_e32 v175, 0xffff0000, v230
	v_lshlrev_b32_e32 v176, 16, v226
	v_and_b32_e32 v177, 0xffff0000, v226
	v_pk_add_f32 v[178:179], v[174:175], v[176:177] neg_lo:[0,1] neg_hi:[0,1]
	v_pk_add_f32 v[172:173], v[172:173], v[178:179]
	v_pk_fma_f32 v[182:183], v[172:173], s[72:73], v[174:175] neg_lo:[0,0,1] neg_hi:[0,0,1]
	v_cvt_pk_bf16_f32 v187, v182, v183
	global_store_dword v105, v187, s[76:77] offset:3072
	v_lshlrev_b32_e32 v174, 16, v231
	v_and_b32_e32 v175, 0xffff0000, v231
	v_lshlrev_b32_e32 v176, 16, v227
	v_and_b32_e32 v177, 0xffff0000, v227
	v_pk_add_f32 v[178:179], v[174:175], v[176:177] neg_lo:[0,1] neg_hi:[0,1]
	v_pk_add_f32 v[172:173], v[172:173], v[178:179]
	v_pk_fma_f32 v[182:183], v[172:173], s[72:73], v[174:175] neg_lo:[0,0,1] neg_hi:[0,0,1]
	v_cvt_pk_bf16_f32 v184, v182, v183
	s_add_u32 s76, s76, 0x2000
	s_addc_u32 s77, s77, 0
	s_waitcnt vmcnt(40)
	global_store_dword v105, v184, s[76:77] offset:-3072
	v_lshlrev_b32_e32 v174, 16, v232
	v_and_b32_e32 v175, 0xffff0000, v232
	v_lshlrev_b32_e32 v176, 16, v228
	v_and_b32_e32 v177, 0xffff0000, v228
	v_pk_add_f32 v[178:179], v[174:175], v[176:177] neg_lo:[0,1] neg_hi:[0,1]
	v_pk_add_f32 v[172:173], v[172:173], v[178:179]
	v_pk_fma_f32 v[182:183], v[172:173], s[72:73], v[174:175] neg_lo:[0,0,1] neg_hi:[0,0,1]
	v_cvt_pk_bf16_f32 v185, v182, v183
	global_store_dword v105, v185, s[76:77] offset:-1024
	v_lshlrev_b32_e32 v174, 16, v233
	v_and_b32_e32 v175, 0xffff0000, v233
	v_lshlrev_b32_e32 v176, 16, v229
	v_and_b32_e32 v177, 0xffff0000, v229
	v_pk_add_f32 v[178:179], v[174:175], v[176:177] neg_lo:[0,1] neg_hi:[0,1]
	v_pk_add_f32 v[172:173], v[172:173], v[178:179]
	v_pk_fma_f32 v[182:183], v[172:173], s[72:73], v[174:175] neg_lo:[0,0,1] neg_hi:[0,0,1]
	v_cvt_pk_bf16_f32 v186, v182, v183
	global_store_dword v105, v186, s[76:77] offset:1024
	v_lshlrev_b32_e32 v174, 16, v234
	v_and_b32_e32 v175, 0xffff0000, v234
	v_lshlrev_b32_e32 v176, 16, v230
	v_and_b32_e32 v177, 0xffff0000, v230
	v_pk_add_f32 v[178:179], v[174:175], v[176:177] neg_lo:[0,1] neg_hi:[0,1]
	v_pk_add_f32 v[172:173], v[172:173], v[178:179]
	v_pk_fma_f32 v[182:183], v[172:173], s[72:73], v[174:175] neg_lo:[0,0,1] neg_hi:[0,0,1]
	v_cvt_pk_bf16_f32 v187, v182, v183
	global_store_dword v105, v187, s[76:77] offset:3072
	v_lshlrev_b32_e32 v174, 16, v235
	v_and_b32_e32 v175, 0xffff0000, v235
	v_lshlrev_b32_e32 v176, 16, v231
	v_and_b32_e32 v177, 0xffff0000, v231
	v_pk_add_f32 v[178:179], v[174:175], v[176:177] neg_lo:[0,1] neg_hi:[0,1]
	v_pk_add_f32 v[172:173], v[172:173], v[178:179]
	v_pk_fma_f32 v[182:183], v[172:173], s[72:73], v[174:175] neg_lo:[0,0,1] neg_hi:[0,0,1]
	v_cvt_pk_bf16_f32 v184, v182, v183
	s_add_u32 s76, s76, 0x2000
	s_addc_u32 s77, s77, 0
	global_store_dword v105, v184, s[76:77] offset:-3072
	v_lshlrev_b32_e32 v174, 16, v236
	v_and_b32_e32 v175, 0xffff0000, v236
	v_lshlrev_b32_e32 v176, 16, v232
	v_and_b32_e32 v177, 0xffff0000, v232
	v_pk_add_f32 v[178:179], v[174:175], v[176:177] neg_lo:[0,1] neg_hi:[0,1]
	v_pk_add_f32 v[172:173], v[172:173], v[178:179]
	v_pk_fma_f32 v[182:183], v[172:173], s[72:73], v[174:175] neg_lo:[0,0,1] neg_hi:[0,0,1]
	v_cvt_pk_bf16_f32 v185, v182, v183
	global_store_dword v105, v185, s[76:77] offset:-1024
	v_lshlrev_b32_e32 v174, 16, v237
	v_and_b32_e32 v175, 0xffff0000, v237
	v_lshlrev_b32_e32 v176, 16, v233
	v_and_b32_e32 v177, 0xffff0000, v233
	v_pk_add_f32 v[178:179], v[174:175], v[176:177] neg_lo:[0,1] neg_hi:[0,1]
	v_pk_add_f32 v[172:173], v[172:173], v[178:179]
	v_pk_fma_f32 v[182:183], v[172:173], s[72:73], v[174:175] neg_lo:[0,0,1] neg_hi:[0,0,1]
	v_cvt_pk_bf16_f32 v186, v182, v183
	global_store_dword v105, v186, s[76:77] offset:1024
	v_lshlrev_b32_e32 v174, 16, v238
	v_and_b32_e32 v175, 0xffff0000, v238
	v_lshlrev_b32_e32 v176, 16, v234
	v_and_b32_e32 v177, 0xffff0000, v234
	v_pk_add_f32 v[178:179], v[174:175], v[176:177] neg_lo:[0,1] neg_hi:[0,1]
	v_pk_add_f32 v[172:173], v[172:173], v[178:179]
	v_pk_fma_f32 v[182:183], v[172:173], s[72:73], v[174:175] neg_lo:[0,0,1] neg_hi:[0,0,1]
	v_cvt_pk_bf16_f32 v187, v182, v183
	global_store_dword v105, v187, s[76:77] offset:3072
	s_branch .Lmx_pool_done

; __device__ __forceinline__ unsigned pk2(float lo, float hi) { f32x2v v = {lo, hi}; b16x2v b = __builtin_convertvector(v, b16x2v); return __builtin_bit_cast(unsigned, b); }
; __device__ __forceinline__ f32x2v bf2(unsigned v) { return (f32x2v){bflo(v), bfhi(v)}; }
; template <int W>
; __device__ __forceinline__ void pool_prompt_w(const unsigned (&pin)[31], int t0, unsigned* dst  ) {
;     f32x2v s = {0.f, 0.f};
; #pragma unroll
;     for (int i = 0; i < W; ++i) s = s + bf2(pin[15 - i]);
; #pragma unroll
;     for (int t = 0; t < 16; ++t) {
;         if (t > 0) s = s + (bf2(pin[15 + t]) - bf2(pin[15 + t - W]));
;         const float cnt = (float)min(t0 + t + 1, W); const f32x2v cur = bf2(pin[15 + t]);
;         dst[(size_t)t * 512] = pk2(s.x / cnt - cur.x, s.y / cnt - cur.y);
;     }
; }
; __device__ __forceinline__ void mixer_prompt_run(const Args& p, int run, int c2) {
;     ...
;         if (gi == 0) pool_prompt_w<2>(pin, t0, dst); else if (gi == 1) pool_prompt_w<4>(pin, t0, dst); else if (gi == 2) pool_prompt_w<8>(pin, t0, dst); else pool_prompt_w<16>(pin, t0, dst);
.Lmx_ps1_1:
	s_mov_b32 s78, 0x40000000
	s_mov_b32 s79, 0x3f000000
	v_mul_f32_e32 v180, s79, v172
	v_fma_f32 v240, -v180, s78, v172
	v_fma_f32 v180, v240, s79, v180
	v_mul_f32_e32 v181, s79, v173
	v_fma_f32 v240, -v181, s78, v173
	v_fma_f32 v181, v240, s79, v181
	v_pk_add_f32 v[182:183], v[180:181], v[174:175] neg_lo:[0,1] neg_hi:[0,1]
	s_branch .Lmx_pb1_1
.Lmx_ps1_2:
	s_mov_b32 s78, 0x40400000
	s_mov_b32 s79, 0x3eaaaaab
	v_mul_f32_e32 v180, s79, v172
	v_fma_f32 v240, -v180, s78, v172
	v_fma_f32 v180, v240, s79, v180
	v_mul_f32_e32 v181, s79, v173
	v_fma_f32 v240, -v181, s78, v173
	v_fma_f32 v181, v240, s79, v181
	v_pk_add_f32 v[182:183], v[180:181], v[174:175] neg_lo:[0,1] neg_hi:[0,1]
	s_branch .Lmx_pb1_2
.Lmx_pool2:
	v_lshlrev_b32_e32 v172, 16, v223
	v_and_b32_e32 v173, 0xffff0000, v223
	v_lshlrev_b32_e32 v176, 16, v222
	v_and_b32_e32 v177, 0xffff0000, v222
	v_pk_add_f32 v[172:173], v[172:173], v[176:177]
	v_lshlrev_b32_e32 v176, 16, v221
	v_and_b32_e32 v177, 0xffff0000, v221
	v_pk_add_f32 v[172:173], v[172:173], v[176:177]
	v_lshlrev_b32_e32 v176, 16, v220
	v_and_b32_e32 v177, 0xffff0000, v220
	v_pk_add_f32 v[172:173], v[172:173], v[176:177]
	v_lshlrev_b32_e32 v176, 16, v219
	v_and_b32_e32 v177, 0xffff0000, v219
	v_pk_add_f32 v[172:173], v[172:173], v[176:177]
	v_lshlrev_b32_e32 v176, 16, v218
	v_and_b32_e32 v177, 0xffff0000, v218
	v_pk_add_f32 v[172:173], v[172:173], v[176:177]
	v_lshlrev_b32_e32 v176, 16, v217
	v_and_b32_e32 v177, 0xffff0000, v217
	v_pk_add_f32 v[172:173], v[172:173], v[176:177]
	v_lshlrev_b32_e32 v176, 16, v216
	v_and_b32_e32 v177, 0xffff0000, v216
	v_pk_add_f32 v[172:173], v[172:173], v[176:177]
	v_lshlrev_b32_e32 v174, 16, v223
	v_and_b32_e32 v175, 0xffff0000, v223
	s_cmp_eq_u32 s64, 0
	s_cbranch_scc1 .Lmx_ps2_0
	v_pk_fma_f32 v[182:183], v[172:173], s[72:73], v[174:175] neg_lo:[0,0,1] neg_hi:[0,0,1]
.Lmx_pb2_0:
	v_cvt_pk_bf16_f32 v184, v182, v183
	global_store_dword v105, v184, s[76:77] offset:-3072
	v_lshlrev_b32_e32 v174, 16, v224
	v_and_b32_e32 v175, 0xffff0000, v224
	v_lshlrev_b32_e32 v176, 16, v216
	v_and_b32_e32 v177, 0xffff0000, v216
	v_pk_add_f32 v[178:179], v[174:175], v[176:177] neg_lo:[0,1] neg_hi:[0,1]
	v_pk_add_f32 v[172:173], v[172:173], v[178:179]
	s_cmp_eq_u32 s64, 0
	s_cbranch_scc1 .Lmx_ps2_1
	v_pk_fma_f32 v[182:183], v[172:173], s[72:73], v[174:175] neg_lo:[0,0,1] neg_hi:[0,0,1]
.Lmx_pb2_1:
	v_cvt_pk_bf16_f32 v185, v182, v183
	global_store_dword v105, v185, s[76:77] offset:-1024
	v_lshlrev_b32_e32 v174, 16, v225
	v_and_b32_e32 v175, 0xffff0000, v225
	v_lshlrev_b32_e32 v176, 16, v217
	v_and_b32_e32 v177, 0xffff0000, v217
	v_pk_add_f32 v[178:179], v[174:175], v[176:177] neg_lo:[0,1] neg_hi:[0,1]
	v_pk_add_f32 v[172:173], v[172:173], v[178:179]
	s_cmp_eq_u32 s64, 0
	s_cbranch_scc1 .Lmx_ps2_2
	v_pk_fma_f32 v[182:183], v[172:173], s[72:73], v[174:175] neg_lo:[0,0,1] neg_hi:[0,0,1]
.Lmx_pb2_2:
	v_cvt_pk_bf16_f32 v186, v182, v183
	global_store_dword v105, v186, s[76:77] offset:1024
	v_lshlrev_b32_e32 v174, 16, v226
	v_and_b32_e32 v175, 0xffff0000, v226
	v_lshlrev_b32_e32 v176, 16, v218
	v_and_b32_e32 v177, 0xffff0000, v218
	v_pk_add_f32 v[178:179], v[174:175], v[176:177] neg_lo:[0,1] neg_hi:[0,1]
	v_pk_add_f32 v[172:173], v[172:173], v[178:179]
	s_cmp_eq_u32 s64, 0
	s_cbranch_scc1 .Lmx_ps2_3
	v_pk_fma_f32 v[182:183], v[172:173], s[72:73], v[174:175] neg_lo:[0,0,1] neg_hi:[0,0,1]
.Lmx_pb2_3:
	v_cvt_pk_bf16_f32 v187, v182, v183
	global_store_dword v105, v187, s[76:77] offset:3072
	v_lshlrev_b32_e32 v174, 16, v227
	v_and_b32_e32 v175, 0xffff0000, v227
	v_lshlrev_b32_e32 v176, 16, v219
	v_and_b32_e32 v177, 0xffff0000, v219
	v_pk_add_f32 v[178:179], v[174:175], v[176:177] neg_lo:[0,1] neg_hi:[0,1]
	v_pk_add_f32 v[172:173], v[172:173], v[178:179]
	s_cmp_eq_u32 s64, 0
	s_cbranch_scc1 .Lmx_ps2_4
	v_pk_fma_f32 v[182:183], v[172:173], s[72:73], v[174:175] neg_lo:[0,0,1] neg_hi:[0,0,1]
.Lmx_pb2_4:
	v_cvt_pk_bf16_f32 v184, v182, v183
	s_add_u32 s76, s76, 0x2000
	s_addc_u32 s77, s77, 0
	global_store_dword v105, v184, s[76:77] offset:-3072
	v_lshlrev_b32_e32 v174, 16, v228
	v_and_b32_e32 v175, 0xffff0000, v228
	v_lshlrev_b32_e32 v176, 16, v220
	v_and_b32_e32 v177, 0xffff0000, v220
	v_pk_add_f32 v[178:179], v[174:175], v[176:177] neg_lo:[0,1] neg_hi:[0,1]
	v_pk_add_f32 v[172:173], v[172:173], v[178:179]
	s_cmp_eq_u32 s64, 0
	s_cbranch_scc1 .Lmx_ps2_5
	v_pk_fma_f32 v[182:183], v[172:173], s[72:73], v[174:175] neg_lo:[0,0,1] neg_hi:[0,0,1]
; __device__ __forceinline__ unsigned pk2(float lo, float hi) { f32x2v v = {lo, hi}; b16x2v b = __builtin_convertvector(v, b16x2v); return __builtin_bit_cast(unsigned, b); }
; __device__ __forceinline__ f32x2v bf2(unsigned v) { return (f32x2v){bflo(v), bfhi(v)}; }
; template <int W>
; __device__ __forceinline__ void pool_prompt_w(const unsigned (&pin)[31], int t0, unsigned* dst  ) {
;     f32x2v s = {0.f, 0.f};
; #pragma unroll
;     for (int i = 0; i < W; ++i) s = s + bf2(pin[15 - i]);
; #pragma unroll
;     for (int t = 0; t < 16; ++t) {
;         if (t > 0) s = s + (bf2(pin[15 + t]) - bf2(pin[15 + t - W]));
;         const float cnt = (float)min(t0 + t + 1, W); const f32x2v cur = bf2(pin[15 + t]);
;         dst[(size_t)t * 512] = pk2(s.x / cnt - cur.x, s.y / cnt - cur.y);
;     }
; }
; __device__ __forceinline__ void mixer_prompt_run(const Args& p, int run, int c2) {
;     ...
;         if (gi == 0) pool_prompt_w<2>(pin, t0, dst); else if (gi == 1) pool_prompt_w<4>(pin, t0, dst); else if (gi == 2) pool_prompt_w<8>(pin, t0, dst); else pool_prompt_w<16>(pin, t0, dst);
.Lmx_pb2_5:
	v_cvt_pk_bf16_f32 v185, v182, v183
	global_store_dword v105, v185, s[76:77] offset:-1024
	v_lshlrev_b32_e32 v174, 16, v229
	v_and_b32_e32 v175, 0xffff0000, v229
	v_lshlrev_b32_e32 v176, 16, v221
	v_and_b32_e32 v177, 0xffff0000, v221
	v_pk_add_f32 v[178:179], v[174:175], v[176:177] neg_lo:[0,1] neg_hi:[0,1]
	v_pk_add_f32 v[172:173], v[172:173], v[178:179]
	s_cmp_eq_u32 s64, 0
	s_cbranch_scc1 .Lmx_ps2_6
	v_pk_fma_f32 v[182:183], v[172:173], s[72:73], v[174:175] neg_lo:[0,0,1] neg_hi:[0,0,1]
.Lmx_pb2_6:
	v_cvt_pk_bf16_f32 v186, v182, v183
	global_store_dword v105, v186, s[76:77] offset:1024
	v_lshlrev_b32_e32 v174, 16, v230
	v_and_b32_e32 v175, 0xffff0000, v230
	v_lshlrev_b32_e32 v176, 16, v222
	v_and_b32_e32 v177, 0xffff0000, v222
	v_pk_add_f32 v[178:179], v[174:175], v[176:177] neg_lo:[0,1] neg_hi:[0,1]
	v_pk_add_f32 v[172:173], v[172:173], v[178:179]
	v_pk_fma_f32 v[182:183], v[172:173], s[72:73], v[174:175] neg_lo:[0,0,1] neg_hi:[0,0,1]
	v_cvt_pk_bf16_f32 v187, v182, v183
	global_store_dword v105, v187, s[76:77] offset:3072
	v_lshlrev_b32_e32 v174, 16, v231
	v_and_b32_e32 v175, 0xffff0000, v231
	v_lshlrev_b32_e32 v176, 16, v223
	v_and_b32_e32 v177, 0xffff0000, v223
	v_pk_add_f32 v[178:179], v[174:175], v[176:177] neg_lo:[0,1] neg_hi:[0,1]
	v_pk_add_f32 v[172:173], v[172:173], v[178:179]
	v_pk_fma_f32 v[182:183], v[172:173], s[72:73], v[174:175] neg_lo:[0,0,1] neg_hi:[0,0,1]
	v_cvt_pk_bf16_f32 v184, v182, v183
	s_add_u32 s76, s76, 0x2000
	s_addc_u32 s77, s77, 0
	s_waitcnt vmcnt(40)
	global_store_dword v105, v184, s[76:77] offset:-3072
	v_lshlrev_b32_e32 v174, 16, v232
	v_and_b32_e32 v175, 0xffff0000, v232
	v_lshlrev_b32_e32 v176, 16, v224
	v_and_b32_e32 v177, 0xffff0000, v224
	v_pk_add_f32 v[178:179], v[174:175], v[176:177] neg_lo:[0,1] neg_hi:[0,1]
	v_pk_add_f32 v[172:173], v[172:173], v[178:179]
	v_pk_fma_f32 v[182:183], v[172:173], s[72:73], v[174:175] neg_lo:[0,0,1] neg_hi:[0,0,1]
	v_cvt_pk_bf16_f32 v185, v182, v183
	global_store_dword v105, v185, s[76:77] offset:-1024
	v_lshlrev_b32_e32 v174, 16, v233
	v_and_b32_e32 v175, 0xffff0000, v233
	v_lshlrev_b32_e32 v176, 16, v225
	v_and_b32_e32 v177, 0xffff0000, v225
	v_pk_add_f32 v[178:179], v[174:175], v[176:177] neg_lo:[0,1] neg_hi:[0,1]
	v_pk_add_f32 v[172:173], v[172:173], v[178:179]
	v_pk_fma_f32 v[182:183], v[172:173], s[72:73], v[174:175] neg_lo:[0,0,1] neg_hi:[0,0,1]
	v_cvt_pk_bf16_f32 v186, v182, v183
	global_store_dword v105, v186, s[76:77] offset:1024
	v_lshlrev_b32_e32 v174, 16, v234
	v_and_b32_e32 v175, 0xffff0000, v234
	v_lshlrev_b32_e32 v176, 16, v226
	v_and_b32_e32 v177, 0xffff0000, v226
	v_pk_add_f32 v[178:179], v[174:175], v[176:177] neg_lo:[0,1] neg_hi:[0,1]
	v_pk_add_f32 v[172:173], v[172:173], v[178:179]
	v_pk_fma_f32 v[182:183], v[172:173], s[72:73], v[174:175] neg_lo:[0,0,1] neg_hi:[0,0,1]
	v_cvt_pk_bf16_f32 v187, v182, v183
	global_store_dword v105, v187, s[76:77] offset:3072
	v_lshlrev_b32_e32 v174, 16, v235
	v_and_b32_e32 v175, 0xffff0000, v235
	v_lshlrev_b32_e32 v176, 16, v227
	v_and_b32_e32 v177, 0xffff0000, v227
	v_pk_add_f32 v[178:179], v[174:175], v[176:177] neg_lo:[0,1] neg_hi:[0,1]
	v_pk_add_f32 v[172:173], v[172:173], v[178:179]
	v_pk_fma_f32 v[182:183], v[172:173], s[72:73], v[174:175] neg_lo:[0,0,1] neg_hi:[0,0,1]
	v_cvt_pk_bf16_f32 v184, v182, v183
	s_add_u32 s76, s76, 0x2000
	s_addc_u32 s77, s77, 0
	global_store_dword v105, v184, s[76:77] offset:-3072
	v_lshlrev_b32_e32 v174, 16, v236
	v_and_b32_e32 v175, 0xffff0000, v236
	v_lshlrev_b32_e32 v176, 16, v228
	v_and_b32_e32 v177, 0xffff0000, v228
	v_pk_add_f32 v[178:179], v[174:175], v[176:177] neg_lo:[0,1] neg_hi:[0,1]
	v_pk_add_f32 v[172:173], v[172:173], v[178:179]
	v_pk_fma_f32 v[182:183], v[172:173], s[72:73], v[174:175] neg_lo:[0,0,1] neg_hi:[0,0,1]
	v_cvt_pk_bf16_f32 v185, v182, v183
	global_store_dword v105, v185, s[76:77] offset:-1024
	v_lshlrev_b32_e32 v174, 16, v237
	v_and_b32_e32 v175, 0xffff0000, v237
	v_lshlrev_b32_e32 v176, 16, v229
	v_and_b32_e32 v177, 0xffff0000, v229
	v_pk_add_f32 v[178:179], v[174:175], v[176:177] neg_lo:[0,1] neg_hi:[0,1]
	v_pk_add_f32 v[172:173], v[172:173], v[178:179]
	v_pk_fma_f32 v[182:183], v[172:173], s[72:73], v[174:175] neg_lo:[0,0,1] neg_hi:[0,0,1]
	v_cvt_pk_bf16_f32 v186, v182, v183
	global_store_dword v105, v186, s[76:77] offset:1024
	v_lshlrev_b32_e32 v174, 16, v238
	v_and_b32_e32 v175, 0xffff0000, v238
	v_lshlrev_b32_e32 v176, 16, v230
	v_and_b32_e32 v177, 0xffff0000, v230
	v_pk_add_f32 v[178:179], v[174:175], v[176:177] neg_lo:[0,1] neg_hi:[0,1]
	v_pk_add_f32 v[172:173], v[172:173], v[178:179]
	v_pk_fma_f32 v[182:183], v[172:173], s[72:73], v[174:175] neg_lo:[0,0,1] neg_hi:[0,0,1]
	v_cvt_pk_bf16_f32 v187, v182, v183
	global_store_dword v105, v187, s[76:77] offset:3072
	s_branch .Lmx_pool_done

; __device__ __forceinline__ unsigned pk2(float lo, float hi) { f32x2v v = {lo, hi}; b16x2v b = __builtin_convertvector(v, b16x2v); return __builtin_bit_cast(unsigned, b); }
; __device__ __forceinline__ f32x2v bf2(unsigned v) { return (f32x2v){bflo(v), bfhi(v)}; }
; template <int W>
; __device__ __forceinline__ void pool_prompt_w(const unsigned (&pin)[31], int t0, unsigned* dst  ) {
;     f32x2v s = {0.f, 0.f};
; #pragma unroll
;     for (int i = 0; i < W; ++i) s = s + bf2(pin[15 - i]);
; #pragma unroll
;     for (int t = 0; t < 16; ++t) {
;         if (t > 0) s = s + (bf2(pin[15 + t]) - bf2(pin[15 + t - W]));
;         const float cnt = (float)min(t0 + t + 1, W); const f32x2v cur = bf2(pin[15 + t]);
;         dst[(size_t)t * 512] = pk2(s.x / cnt - cur.x, s.y / cnt - cur.y);
;     }
; }
; __device__ __forceinline__ void mixer_prompt_run(const Args& p, int run, int c2) {
;     ...
;         if (gi == 0) pool_prompt_w<2>(pin, t0, dst); else if (gi == 1) pool_prompt_w<4>(pin, t0, dst); else if (gi == 2) pool_prompt_w<8>(pin, t0, dst); else pool_prompt_w<16>(pin, t0, dst);
.Lmx_ps2_3:
	s_mov_b32 s78, 0x40800000
	s_mov_b32 s79, 0x3e800000
	v_mul_f32_e32 v180, s79, v172
	v_fma_f32 v240, -v180, s78, v172
	v_fma_f32 v180, v240, s79, v180
	v_mul_f32_e32 v181, s79, v173
	v_fma_f32 v240, -v181, s78, v173
	v_fma_f32 v181, v240, s79, v181
	v_pk_add_f32 v[182:183], v[180:181], v[174:175] neg_lo:[0,1] neg_hi:[0,1]
	s_branch .Lmx_pb2_3
.Lmx_ps2_4:
	s_mov_b32 s78, 0x40a00000
	s_mov_b32 s79, 0x3e4ccccd
	v_mul_f32_e32 v180, s79, v172
	v_fma_f32 v240, -v180, s78, v172
	v_fma_f32 v180, v240, s79, v180
	v_mul_f32_e32 v181, s79, v173
	v_fma_f32 v240, -v181, s78, v173
	v_fma_f32 v181, v240, s79, v181
	v_pk_add_f32 v[182:183], v[180:181], v[174:175] neg_lo:[0,1] neg_hi:[0,1]
	s_branch .Lmx_pb2_4
.Lmx_ps2_5:
	s_mov_b32 s78, 0x40c00000
	s_mov_b32 s79, 0x3e2aaaab
	v_mul_f32_e32 v180, s79, v172
	v_fma_f32 v240, -v180, s78, v172
	v_fma_f32 v180, v240, s79, v180
	v_mul_f32_e32 v181, s79, v173
	v_fma_f32 v240, -v181, s78, v173
	v_fma_f32 v181, v240, s79, v181
	v_pk_add_f32 v[182:183], v[180:181], v[174:175] neg_lo:[0,1] neg_hi:[0,1]
	s_branch .Lmx_pb2_5
.Lmx_ps2_6:
	s_mov_b32 s78, 0x40e00000
	s_mov_b32 s79, 0x3e124925
	v_mul_f32_e32 v180, s79, v172
	v_fma_f32 v240, -v180, s78, v172
	v_fma_f32 v180, v240, s79, v180
	v_mul_f32_e32 v181, s79, v173
	v_fma_f32 v240, -v181, s78, v173
	v_fma_f32 v181, v240, s79, v181
	v_pk_add_f32 v[182:183], v[180:181], v[174:175] neg_lo:[0,1] neg_hi:[0,1]
	s_branch .Lmx_pb2_6
.Lmx_pool3:
	v_lshlrev_b32_e32 v172, 16, v223
	v_and_b32_e32 v173, 0xffff0000, v223
	v_lshlrev_b32_e32 v176, 16, v222
	v_and_b32_e32 v177, 0xffff0000, v222
	v_pk_add_f32 v[172:173], v[172:173], v[176:177]
	v_lshlrev_b32_e32 v176, 16, v221
	v_and_b32_e32 v177, 0xffff0000, v221
	v_pk_add_f32 v[172:173], v[172:173], v[176:177]
	v_lshlrev_b32_e32 v176, 16, v220
	v_and_b32_e32 v177, 0xffff0000, v220
	v_pk_add_f32 v[172:173], v[172:173], v[176:177]
	v_lshlrev_b32_e32 v176, 16, v219
	v_and_b32_e32 v177, 0xffff0000, v219
	v_pk_add_f32 v[172:173], v[172:173], v[176:177]
	v_lshlrev_b32_e32 v176, 16, v218
	v_and_b32_e32 v177, 0xffff0000, v218
	v_pk_add_f32 v[172:173], v[172:173], v[176:177]
	v_lshlrev_b32_e32 v176, 16, v217
	v_and_b32_e32 v177, 0xffff0000, v217
	v_pk_add_f32 v[172:173], v[172:173], v[176:177]
	v_lshlrev_b32_e32 v176, 16, v216
	v_and_b32_e32 v177, 0xffff0000, v216
	v_pk_add_f32 v[172:173], v[172:173], v[176:177]
	v_lshlrev_b32_e32 v176, 16, v215
	v_and_b32_e32 v177, 0xffff0000, v215
	v_pk_add_f32 v[172:173], v[172:173], v[176:177]
	v_lshlrev_b32_e32 v176, 16, v214
	v_and_b32_e32 v177, 0xffff0000, v214
	v_pk_add_f32 v[172:173], v[172:173], v[176:177]
	v_lshlrev_b32_e32 v176, 16, v213
	v_and_b32_e32 v177, 0xffff0000, v213
	v_pk_add_f32 v[172:173], v[172:173], v[176:177]
	v_lshlrev_b32_e32 v176, 16, v212
	v_and_b32_e32 v177, 0xffff0000, v212
	v_pk_add_f32 v[172:173], v[172:173], v[176:177]
	v_lshlrev_b32_e32 v176, 16, v211
	v_and_b32_e32 v177, 0xffff0000, v211
	v_pk_add_f32 v[172:173], v[172:173], v[176:177]
	v_lshlrev_b32_e32 v176, 16, v210
	v_and_b32_e32 v177, 0xffff0000, v210
	v_pk_add_f32 v[172:173], v[172:173], v[176:177]
	v_lshlrev_b32_e32 v176, 16, v209
	v_and_b32_e32 v177, 0xffff0000, v209
	v_pk_add_f32 v[172:173], v[172:173], v[176:177]
	v_lshlrev_b32_e32 v176, 16, v208
	v_and_b32_e32 v177, 0xffff0000, v208
	v_pk_add_f32 v[172:173], v[172:173], v[176:177]
	v_lshlrev_b32_e32 v174, 16, v223
	v_and_b32_e32 v175, 0xffff0000, v223
	s_cmp_eq_u32 s64, 0
	s_cbranch_scc1 .Lmx_ps3_0
	v_pk_fma_f32 v[182:183], v[172:173], s[72:73], v[174:175] neg_lo:[0,0,1] neg_hi:[0,0,1]
.Lmx_pb3_0:
	v_cvt_pk_bf16_f32 v184, v182, v183
	global_store_dword v105, v184, s[76:77] offset:-3072
	v_lshlrev_b32_e32 v174, 16, v224
	v_and_b32_e32 v175, 0xffff0000, v224
	v_lshlrev_b32_e32 v176, 16, v208
	v_and_b32_e32 v177, 0xffff0000, v208
	v_pk_add_f32 v[178:179], v[174:175], v[176:177] neg_lo:[0,1] neg_hi:[0,1]
	v_pk_add_f32 v[172:173], v[172:173], v[178:179]
	s_cmp_eq_u32 s64, 0
	s_cbranch_scc1 .Lmx_ps3_1
	v_pk_fma_f32 v[182:183], v[172:173], s[72:73], v[174:175] neg_lo:[0,0,1] neg_hi:[0,0,1]
.Lmx_pb3_1:
	v_cvt_pk_bf16_f32 v185, v182, v183
	global_store_dword v105, v185, s[76:77] offset:-1024
	v_lshlrev_b32_e32 v174, 16, v225
	v_and_b32_e32 v175, 0xffff0000, v225
	v_lshlrev_b32_e32 v176, 16, v209
	v_and_b32_e32 v177, 0xffff0000, v209
	v_pk_add_f32 v[178:179], v[174:175], v[176:177] neg_lo:[0,1] neg_hi:[0,1]
	v_pk_add_f32 v[172:173], v[172:173], v[178:179]
	s_cmp_eq_u32 s64, 0
	s_cbranch_scc1 .Lmx_ps3_2
	v_pk_fma_f32 v[182:183], v[172:173], s[72:73], v[174:175] neg_lo:[0,0,1] neg_hi:[0,0,1]
.Lmx_pb3_2:
	v_cvt_pk_bf16_f32 v186, v182, v183
	global_store_dword v105, v186, s[76:77] offset:1024
	v_lshlrev_b32_e32 v174, 16, v226
	v_and_b32_e32 v175, 0xffff0000, v226
	v_lshlrev_b32_e32 v176, 16, v210
	v_and_b32_e32 v177, 0xffff0000, v210
	v_pk_add_f32 v[178:179], v[174:175], v[176:177] neg_lo:[0,1] neg_hi:[0,1]
	v_pk_add_f32 v[172:173], v[172:173], v[178:179]
	s_cmp_eq_u32 s64, 0
	s_cbranch_scc1 .Lmx_ps3_3
	v_pk_fma_f32 v[182:183], v[172:173], s[72:73], v[174:175] neg_lo:[0,0,1] neg_hi:[0,0,1]
.Lmx_pb3_3:
	v_cvt_pk_bf16_f32 v187, v182, v183
	global_store_dword v105, v187, s[76:77] offset:3072
	v_lshlrev_b32_e32 v174, 16, v227
	v_and_b32_e32 v175, 0xffff0000, v227
	v_lshlrev_b32_e32 v176, 16, v211
	v_and_b32_e32 v177, 0xffff0000, v211
	v_pk_add_f32 v[178:179], v[174:175], v[176:177] neg_lo:[0,1] neg_hi:[0,1]
	v_pk_add_f32 v[172:173], v[172:173], v[178:179]
	s_cmp_eq_u32 s64, 0
	s_cbranch_scc1 .Lmx_ps3_4
	v_pk_fma_f32 v[182:183], v[172:173], s[72:73], v[174:175] neg_lo:[0,0,1] neg_hi:[0,0,1]
; __device__ __forceinline__ unsigned pk2(float lo, float hi) { f32x2v v = {lo, hi}; b16x2v b = __builtin_convertvector(v, b16x2v); return __builtin_bit_cast(unsigned, b); }
; __device__ __forceinline__ f32x2v bf2(unsigned v) { return (f32x2v){bflo(v), bfhi(v)}; }
; template <int W>
; __device__ __forceinline__ void pool_prompt_w(const unsigned (&pin)[31], int t0, unsigned* dst  ) {
;     f32x2v s = {0.f, 0.f};
; #pragma unroll
;     for (int i = 0; i < W; ++i) s = s + bf2(pin[15 - i]);
; #pragma unroll
;     for (int t = 0; t < 16; ++t) {
;         if (t > 0) s = s + (bf2(pin[15 + t]) - bf2(pin[15 + t - W]));
;         const float cnt = (float)min(t0 + t + 1, W); const f32x2v cur = bf2(pin[15 + t]);
;         dst[(size_t)t * 512] = pk2(s.x / cnt - cur.x, s.y / cnt - cur.y);
;     }
; }
; __device__ __forceinline__ void mixer_prompt_run(const Args& p, int run, int c2) {
;     ...
;         if (gi == 0) pool_prompt_w<2>(pin, t0, dst); else if (gi == 1) pool_prompt_w<4>(pin, t0, dst); else if (gi == 2) pool_prompt_w<8>(pin, t0, dst); else pool_prompt_w<16>(pin, t0, dst);
.Lmx_pb3_4:
	v_cvt_pk_bf16_f32 v184, v182, v183
	s_add_u32 s76, s76, 0x2000
	s_addc_u32 s77, s77, 0
	global_store_dword v105, v184, s[76:77] offset:-3072
	v_lshlrev_b32_e32 v174, 16, v228
	v_and_b32_e32 v175, 0xffff0000, v228
	v_lshlrev_b32_e32 v176, 16, v212
	v_and_b32_e32 v177, 0xffff0000, v212
	v_pk_add_f32 v[178:179], v[174:175], v[176:177] neg_lo:[0,1] neg_hi:[0,1]
	v_pk_add_f32 v[172:173], v[172:173], v[178:179]
	s_cmp_eq_u32 s64, 0
	s_cbranch_scc1 .Lmx_ps3_5
	v_pk_fma_f32 v[182:183], v[172:173], s[72:73], v[174:175] neg_lo:[0,0,1] neg_hi:[0,0,1]
.Lmx_pb3_5:
	v_cvt_pk_bf16_f32 v185, v182, v183
	global_store_dword v105, v185, s[76:77] offset:-1024
	v_lshlrev_b32_e32 v174, 16, v229
	v_and_b32_e32 v175, 0xffff0000, v229
	v_lshlrev_b32_e32 v176, 16, v213
	v_and_b32_e32 v177, 0xffff0000, v213
	v_pk_add_f32 v[178:179], v[174:175], v[176:177] neg_lo:[0,1] neg_hi:[0,1]
	v_pk_add_f32 v[172:173], v[172:173], v[178:179]
	s_cmp_eq_u32 s64, 0
	s_cbranch_scc1 .Lmx_ps3_6
	v_pk_fma_f32 v[182:183], v[172:173], s[72:73], v[174:175] neg_lo:[0,0,1] neg_hi:[0,0,1]
.Lmx_pb3_6:
	v_cvt_pk_bf16_f32 v186, v182, v183
	global_store_dword v105, v186, s[76:77] offset:1024
	v_lshlrev_b32_e32 v174, 16, v230
	v_and_b32_e32 v175, 0xffff0000, v230
	v_lshlrev_b32_e32 v176, 16, v214
	v_and_b32_e32 v177, 0xffff0000, v214
	v_pk_add_f32 v[178:179], v[174:175], v[176:177] neg_lo:[0,1] neg_hi:[0,1]
	v_pk_add_f32 v[172:173], v[172:173], v[178:179]
	s_cmp_eq_u32 s64, 0
	s_cbranch_scc1 .Lmx_ps3_7
	v_pk_fma_f32 v[182:183], v[172:173], s[72:73], v[174:175] neg_lo:[0,0,1] neg_hi:[0,0,1]
.Lmx_pb3_7:
	v_cvt_pk_bf16_f32 v187, v182, v183
	global_store_dword v105, v187, s[76:77] offset:3072
	v_lshlrev_b32_e32 v174, 16, v231
	v_and_b32_e32 v175, 0xffff0000, v231
	v_lshlrev_b32_e32 v176, 16, v215
	v_and_b32_e32 v177, 0xffff0000, v215
	v_pk_add_f32 v[178:179], v[174:175], v[176:177] neg_lo:[0,1] neg_hi:[0,1]
	v_pk_add_f32 v[172:173], v[172:173], v[178:179]
	s_cmp_eq_u32 s64, 0
	s_cbranch_scc1 .Lmx_ps3_8
	v_pk_fma_f32 v[182:183], v[172:173], s[72:73], v[174:175] neg_lo:[0,0,1] neg_hi:[0,0,1]
.Lmx_pb3_8:
	v_cvt_pk_bf16_f32 v184, v182, v183
	s_add_u32 s76, s76, 0x2000
	s_addc_u32 s77, s77, 0
	s_waitcnt vmcnt(40)
	global_store_dword v105, v184, s[76:77] offset:-3072
	v_lshlrev_b32_e32 v174, 16, v232
	v_and_b32_e32 v175, 0xffff0000, v232
	v_lshlrev_b32_e32 v176, 16, v216
	v_and_b32_e32 v177, 0xffff0000, v216
	v_pk_add_f32 v[178:179], v[174:175], v[176:177] neg_lo:[0,1] neg_hi:[0,1]
	v_pk_add_f32 v[172:173], v[172:173], v[178:179]
	s_cmp_eq_u32 s64, 0
	s_cbranch_scc1 .Lmx_ps3_9
	v_pk_fma_f32 v[182:183], v[172:173], s[72:73], v[174:175] neg_lo:[0,0,1] neg_hi:[0,0,1]
.Lmx_pb3_9:
	v_cvt_pk_bf16_f32 v185, v182, v183
	global_store_dword v105, v185, s[76:77] offset:-1024
	v_lshlrev_b32_e32 v174, 16, v233
	v_and_b32_e32 v175, 0xffff0000, v233
	v_lshlrev_b32_e32 v176, 16, v217
	v_and_b32_e32 v177, 0xffff0000, v217
	v_pk_add_f32 v[178:179], v[174:175], v[176:177] neg_lo:[0,1] neg_hi:[0,1]
	v_pk_add_f32 v[172:173], v[172:173], v[178:179]
	s_cmp_eq_u32 s64, 0
	s_cbranch_scc1 .Lmx_ps3_10
	v_pk_fma_f32 v[182:183], v[172:173], s[72:73], v[174:175] neg_lo:[0,0,1] neg_hi:[0,0,1]
.Lmx_pb3_10:
	v_cvt_pk_bf16_f32 v186, v182, v183
	global_store_dword v105, v186, s[76:77] offset:1024
	v_lshlrev_b32_e32 v174, 16, v234
	v_and_b32_e32 v175, 0xffff0000, v234
	v_lshlrev_b32_e32 v176, 16, v218
	v_and_b32_e32 v177, 0xffff0000, v218
	v_pk_add_f32 v[178:179], v[174:175], v[176:177] neg_lo:[0,1] neg_hi:[0,1]
	v_pk_add_f32 v[172:173], v[172:173], v[178:179]
	s_cmp_eq_u32 s64, 0
	s_cbranch_scc1 .Lmx_ps3_11
	v_pk_fma_f32 v[182:183], v[172:173], s[72:73], v[174:175] neg_lo:[0,0,1] neg_hi:[0,0,1]
.Lmx_pb3_11:
	v_cvt_pk_bf16_f32 v187, v182, v183
	global_store_dword v105, v187, s[76:77] offset:3072
	v_lshlrev_b32_e32 v174, 16, v235
	v_and_b32_e32 v175, 0xffff0000, v235
	v_lshlrev_b32_e32 v176, 16, v219
	v_and_b32_e32 v177, 0xffff0000, v219
	v_pk_add_f32 v[178:179], v[174:175], v[176:177] neg_lo:[0,1] neg_hi:[0,1]
	v_pk_add_f32 v[172:173], v[172:173], v[178:179]
	s_cmp_eq_u32 s64, 0
	s_cbranch_scc1 .Lmx_ps3_12
	v_pk_fma_f32 v[182:183], v[172:173], s[72:73], v[174:175] neg_lo:[0,0,1] neg_hi:[0,0,1]
.Lmx_pb3_12:
	v_cvt_pk_bf16_f32 v184, v182, v183
	s_add_u32 s76, s76, 0x2000
	s_addc_u32 s77, s77, 0
	global_store_dword v105, v184, s[76:77] offset:-3072
	v_lshlrev_b32_e32 v174, 16, v236
	v_and_b32_e32 v175, 0xffff0000, v236
	v_lshlrev_b32_e32 v176, 16, v220
	v_and_b32_e32 v177, 0xffff0000, v220
	v_pk_add_f32 v[178:179], v[174:175], v[176:177] neg_lo:[0,1] neg_hi:[0,1]
	v_pk_add_f32 v[172:173], v[172:173], v[178:179]
	s_cmp_eq_u32 s64, 0
	s_cbranch_scc1 .Lmx_ps3_13
	v_pk_fma_f32 v[182:183], v[172:173], s[72:73], v[174:175] neg_lo:[0,0,1] neg_hi:[0,0,1]
.Lmx_pb3_13:
	v_cvt_pk_bf16_f32 v185, v182, v183
	global_store_dword v105, v185, s[76:77] offset:-1024
	v_lshlrev_b32_e32 v174, 16, v237
	v_and_b32_e32 v175, 0xffff0000, v237
	v_lshlrev_b32_e32 v176, 16, v221
	v_and_b32_e32 v177, 0xffff0000, v221
	v_pk_add_f32 v[178:179], v[174:175], v[176:177] neg_lo:[0,1] neg_hi:[0,1]
	v_pk_add_f32 v[172:173], v[172:173], v[178:179]
	s_cmp_eq_u32 s64, 0
	s_cbranch_scc1 .Lmx_ps3_14
	v_pk_fma_f32 v[182:183], v[172:173], s[72:73], v[174:175] neg_lo:[0,0,1] neg_hi:[0,0,1]
.Lmx_pb3_14:
	v_cvt_pk_bf16_f32 v186, v182, v183
	global_store_dword v105, v186, s[76:77] offset:1024
	v_lshlrev_b32_e32 v174, 16, v238
	v_and_b32_e32 v175, 0xffff0000, v238
	v_lshlrev_b32_e32 v176, 16, v222
	v_and_b32_e32 v177, 0xffff0000, v222
	v_pk_add_f32 v[178:179], v[174:175], v[176:177] neg_lo:[0,1] neg_hi:[0,1]
	v_pk_add_f32 v[172:173], v[172:173], v[178:179]
	v_pk_fma_f32 v[182:183], v[172:173], s[72:73], v[174:175] neg_lo:[0,0,1] neg_hi:[0,0,1]
	v_cvt_pk_bf16_f32 v187, v182, v183
	global_store_dword v105, v187, s[76:77] offset:3072
	s_branch .Lmx_pool_done

; __device__ __forceinline__ unsigned pk2(float lo, float hi) { f32x2v v = {lo, hi}; b16x2v b = __builtin_convertvector(v, b16x2v); return __builtin_bit_cast(unsigned, b); }
; __device__ __forceinline__ f32x2v bf2(unsigned v) { return (f32x2v){bflo(v), bfhi(v)}; }
; template <int W>
; __device__ __forceinline__ void pool_prompt_w(const unsigned (&pin)[31], int t0, unsigned* dst  ) {
;     ...
;         const float cnt = (float)min(t0 + t + 1, W); const f32x2v cur = bf2(pin[15 + t]);
;         dst[(size_t)t * 512] = pk2(s.x / cnt - cur.x, s.y / cnt - cur.y);
; __device__ __forceinline__ void mixer_prompt_run(const Args& p, int run, int c2) {
;     ...
;             for (int i = 0; i < 38; ++i) {
;                 const int ti = t0 + 8 * hh - 30 + i; unsigned v = U32[(rowb + (ti >= 0 ? ti : 0)) * 256 + c2]; v = (ti >= 0) ? v : 0u; const f32x2v x = bf2(v);
.Lmx_ps3_7:
	s_mov_b32 s78, 0x41000000
	s_mov_b32 s79, 0x3e000000
	v_mul_f32_e32 v180, s79, v172
	v_fma_f32 v240, -v180, s78, v172
	v_fma_f32 v180, v240, s79, v180
	v_mul_f32_e32 v181, s79, v173
	v_fma_f32 v240, -v181, s78, v173
	v_fma_f32 v181, v240, s79, v181
	v_pk_add_f32 v[182:183], v[180:181], v[174:175] neg_lo:[0,1] neg_hi:[0,1]
	s_branch .Lmx_pb3_7
.Lmx_ps3_8:
	s_mov_b32 s78, 0x41100000
	s_mov_b32 s79, 0x3de38e39
	v_mul_f32_e32 v180, s79, v172
	v_fma_f32 v240, -v180, s78, v172
	v_fma_f32 v180, v240, s79, v180
	v_mul_f32_e32 v181, s79, v173
	v_fma_f32 v240, -v181, s78, v173
	v_fma_f32 v181, v240, s79, v181
	v_pk_add_f32 v[182:183], v[180:181], v[174:175] neg_lo:[0,1] neg_hi:[0,1]
	s_branch .Lmx_pb3_8
.Lmx_ps3_9:
	s_mov_b32 s78, 0x41200000
	s_mov_b32 s79, 0x3dcccccd
	v_mul_f32_e32 v180, s79, v172
	v_fma_f32 v240, -v180, s78, v172
	v_fma_f32 v180, v240, s79, v180
	v_mul_f32_e32 v181, s79, v173
	v_fma_f32 v240, -v181, s78, v173
	v_fma_f32 v181, v240, s79, v181
	v_pk_add_f32 v[182:183], v[180:181], v[174:175] neg_lo:[0,1] neg_hi:[0,1]
	s_branch .Lmx_pb3_9
.Lmx_ps3_10:
	s_mov_b32 s78, 0x41300000
	s_mov_b32 s79, 0x3dba2e8c
	v_mul_f32_e32 v180, s79, v172
	v_fma_f32 v240, -v180, s78, v172
	v_fma_f32 v180, v240, s79, v180
	v_mul_f32_e32 v181, s79, v173
	v_fma_f32 v240, -v181, s78, v173
	v_fma_f32 v181, v240, s79, v181
	v_pk_add_f32 v[182:183], v[180:181], v[174:175] neg_lo:[0,1] neg_hi:[0,1]
	s_branch .Lmx_pb3_10
.Lmx_ps3_11:
	s_mov_b32 s78, 0x41400000
	s_mov_b32 s79, 0x3daaaaab
	v_mul_f32_e32 v180, s79, v172
	v_fma_f32 v240, -v180, s78, v172
	v_fma_f32 v180, v240, s79, v180
	v_mul_f32_e32 v181, s79, v173
	v_fma_f32 v240, -v181, s78, v173
	v_fma_f32 v181, v240, s79, v181
	v_pk_add_f32 v[182:183], v[180:181], v[174:175] neg_lo:[0,1] neg_hi:[0,1]
	s_branch .Lmx_pb3_11
.Lmx_ps3_12:
	s_mov_b32 s78, 0x41500000
	s_mov_b32 s79, 0x3d9d89d9
	v_mul_f32_e32 v180, s79, v172
	v_fma_f32 v240, -v180, s78, v172
	v_fma_f32 v180, v240, s79, v180
	v_mul_f32_e32 v181, s79, v173
	v_fma_f32 v240, -v181, s78, v173
	v_fma_f32 v181, v240, s79, v181
	v_pk_add_f32 v[182:183], v[180:181], v[174:175] neg_lo:[0,1] neg_hi:[0,1]
	s_branch .Lmx_pb3_12
.Lmx_ps3_13:
	s_mov_b32 s78, 0x41600000
	s_mov_b32 s79, 0x3d924925
	v_mul_f32_e32 v180, s79, v172
	v_fma_f32 v240, -v180, s78, v172
	v_fma_f32 v180, v240, s79, v180
	v_mul_f32_e32 v181, s79, v173
	v_fma_f32 v240, -v181, s78, v173
	v_fma_f32 v181, v240, s79, v181
	v_pk_add_f32 v[182:183], v[180:181], v[174:175] neg_lo:[0,1] neg_hi:[0,1]
	s_branch .Lmx_pb3_13
.Lmx_ps3_14:
	s_mov_b32 s78, 0x41700000
	s_mov_b32 s79, 0x3d888889
	v_mul_f32_e32 v180, s79, v172
	v_fma_f32 v240, -v180, s78, v172
	v_fma_f32 v180, v240, s79, v180
	v_mul_f32_e32 v181, s79, v173
	v_fma_f32 v240, -v181, s78, v173
	v_fma_f32 v181, v240, s79, v181
	v_pk_add_f32 v[182:183], v[180:181], v[174:175] neg_lo:[0,1] neg_hi:[0,1]
	s_branch .Lmx_pb3_14
.Lmx_pool_done:
	s_mov_b32 s78, 0xbc800000
	s_mov_b32 s79, 0xbc800000
	s_mov_b32 s80, 0xbfb8aa3b
	s_mov_b32 s81, 0xbfb8aa3b
	s_mov_b32 s86, 0x3f800000
	s_mov_b32 s87, 0x3f800000
	v_mov_b32_e32 v241, 0x3727c5ac
	s_waitcnt vmcnt(30)
	global_load_dword v208, v105, s[66:67] offset:3072
	s_add_u32 s66, s66, 0x2000
	s_addc_u32 s67, s67, 0
	global_load_dword v209, v105, s[66:67] offset:-4096
	global_load_dword v210, v105, s[66:67] offset:-3072
	global_load_dword v211, v105, s[66:67] offset:-2048
	global_load_dword v212, v105, s[66:67] offset:-1024
	global_load_dword v213, v105, s[66:67] offset:0
	global_load_dword v214, v105, s[66:67] offset:1024
	global_load_dword v215, v105, s[66:67] offset:2048
	global_load_dword v216, v105, s[66:67] offset:3072
	s_add_u32 s66, s66, 0x2000
	s_addc_u32 s67, s67, 0
	global_load_dword v217, v105, s[66:67] offset:-4096
	global_load_dword v218, v105, s[66:67] offset:-3072
	global_load_dword v219, v105, s[66:67] offset:-2048
	global_load_dword v220, v105, s[66:67] offset:-1024
	global_load_dword v221, v105, s[66:67] offset:0
	global_load_dword v222, v105, s[66:67] offset:1024
	global_load_dword v223, v105, s[66:67] offset:2048
	global_load_dword v224, v105, s[66:67] offset:3072
	s_add_u32 s66, s66, 0x2000
	s_addc_u32 s67, s67, 0
	global_load_dword v225, v105, s[66:67] offset:-4096
	global_load_dword v226, v105, s[66:67] offset:-3072
	global_load_dword v227, v105, s[66:67] offset:-2048
	global_load_dword v228, v105, s[66:67] offset:-1024
	global_load_dword v229, v105, s[66:67] offset:0
	global_load_dword v230, v105, s[66:67] offset:1024
	global_load_dword v231, v105, s[66:67] offset:2048
	global_load_dword v232, v105, s[66:67] offset:3072
	s_add_u32 s66, s66, 0x2000
	s_addc_u32 s67, s67, 0
	global_load_dword v233, v105, s[66:67] offset:-4096
	global_load_dword v234, v105, s[66:67] offset:-3072
	global_load_dword v235, v105, s[66:67] offset:-2048
	global_load_dword v236, v105, s[66:67] offset:-1024
	global_load_dword v237, v105, s[66:67] offset:0
	global_load_dword v238, v105, s[66:67] offset:1024
	s_waitcnt vmcnt(47)
	s_cbranch_vccnz .Lmx_e0

; __device__ __forceinline__ f32x2v bf2(unsigned v) { return (f32x2v){bflo(v), bfhi(v)}; }
; __device__ __forceinline__ void mixer_prompt_run(const Args& p, int run, int c2) {
;     ...
;             for (int i = 0; i < 38; ++i) {
;                 const int ti = t0 + 8 * hh - 30 + i; unsigned v = U32[(rowb + (ti >= 0 ? ti : 0)) * 256 + c2]; v = (ti >= 0) ? v : 0u; const f32x2v x = bf2(v);
; #pragma unroll
;                 for (int t = 0; t < 8; ++t) { const int j = i - t; if (j >= 0 && j <= 30) a[t] = w[j] * x + a[t]; }
;                 if (i == 18) asm volatile("" ::: "memory");
;             }
.Lmx_b29:
	v_lshlrev_b32_e32 v98, 16, v222
	v_and_b32_e32 v99, 0xffff0000, v222
	v_pk_fma_f32 v[172:173], v[168:169], v[98:99], v[172:173]
	v_pk_fma_f32 v[174:175], v[162:163], v[98:99], v[174:175]
	v_pk_fma_f32 v[176:177], v[160:161], v[98:99], v[176:177]
	v_pk_fma_f32 v[178:179], v[158:159], v[98:99], v[178:179]
	v_pk_fma_f32 v[180:181], v[156:157], v[98:99], v[180:181]
	v_pk_fma_f32 v[182:183], v[154:155], v[98:99], v[182:183]
	v_pk_fma_f32 v[184:185], v[152:153], v[98:99], v[184:185]
	v_pk_fma_f32 v[186:187], v[150:151], v[98:99], v[186:187]
	v_pk_fma_f32 v[188:189], v[148:149], v[98:99], v[188:189]
	v_pk_fma_f32 v[190:191], v[146:147], v[98:99], v[190:191]
	v_pk_fma_f32 v[78:79], v[144:145], v[98:99], v[78:79]
	v_pk_fma_f32 v[80:81], v[142:143], v[98:99], v[80:81]
	v_pk_fma_f32 v[82:83], v[140:141], v[98:99], v[82:83]
	v_pk_fma_f32 v[84:85], v[138:139], v[98:99], v[84:85]
	v_pk_fma_f32 v[86:87], v[136:137], v[98:99], v[86:87]
	v_pk_fma_f32 v[88:89], v[134:135], v[98:99], v[88:89]
	s_waitcnt vmcnt(15)
	v_lshlrev_b32_e32 v96, 16, v223
	v_and_b32_e32 v97, 0xffff0000, v223
	v_pk_fma_f32 v[172:173], v[170:171], v[96:97], v[172:173]
	v_pk_fma_f32 v[174:175], v[168:169], v[96:97], v[174:175]
	v_pk_fma_f32 v[176:177], v[162:163], v[96:97], v[176:177]
	v_pk_fma_f32 v[178:179], v[160:161], v[96:97], v[178:179]
	v_pk_fma_f32 v[180:181], v[158:159], v[96:97], v[180:181]
	v_pk_fma_f32 v[182:183], v[156:157], v[96:97], v[182:183]
	v_pk_fma_f32 v[184:185], v[154:155], v[96:97], v[184:185]
	v_pk_fma_f32 v[186:187], v[152:153], v[96:97], v[186:187]
	v_pk_fma_f32 v[188:189], v[150:151], v[96:97], v[188:189]
	v_pk_fma_f32 v[190:191], v[148:149], v[96:97], v[190:191]
	v_pk_fma_f32 v[78:79], v[146:147], v[96:97], v[78:79]
	v_pk_fma_f32 v[80:81], v[144:145], v[96:97], v[80:81]
	v_pk_fma_f32 v[82:83], v[142:143], v[96:97], v[82:83]
	v_pk_fma_f32 v[84:85], v[140:141], v[96:97], v[84:85]
	v_pk_fma_f32 v[86:87], v[138:139], v[96:97], v[86:87]
	v_pk_fma_f32 v[88:89], v[136:137], v[96:97], v[88:89]
	s_waitcnt vmcnt(14)
	v_lshlrev_b32_e32 v98, 16, v224
	v_and_b32_e32 v99, 0xffff0000, v224
	v_pk_fma_f32 v[174:175], v[170:171], v[98:99], v[174:175]
	v_pk_fma_f32 v[176:177], v[168:169], v[98:99], v[176:177]
	v_pk_fma_f32 v[178:179], v[162:163], v[98:99], v[178:179]
	v_pk_fma_f32 v[180:181], v[160:161], v[98:99], v[180:181]
	v_pk_fma_f32 v[182:183], v[158:159], v[98:99], v[182:183]
	v_pk_fma_f32 v[184:185], v[156:157], v[98:99], v[184:185]
	v_pk_fma_f32 v[186:187], v[154:155], v[98:99], v[186:187]
	v_pk_fma_f32 v[188:189], v[152:153], v[98:99], v[188:189]
	v_pk_fma_f32 v[190:191], v[150:151], v[98:99], v[190:191]
	v_pk_fma_f32 v[78:79], v[148:149], v[98:99], v[78:79]
	v_pk_fma_f32 v[80:81], v[146:147], v[98:99], v[80:81]
	v_pk_fma_f32 v[82:83], v[144:145], v[98:99], v[82:83]
	v_pk_fma_f32 v[84:85], v[142:143], v[98:99], v[84:85]
	v_pk_fma_f32 v[86:87], v[140:141], v[98:99], v[86:87]
	v_pk_fma_f32 v[88:89], v[138:139], v[98:99], v[88:89]
	s_waitcnt vmcnt(13)
	v_lshlrev_b32_e32 v96, 16, v225
	v_and_b32_e32 v97, 0xffff0000, v225
	v_pk_fma_f32 v[176:177], v[170:171], v[96:97], v[176:177]
	v_pk_fma_f32 v[178:179], v[168:169], v[96:97], v[178:179]
	v_pk_fma_f32 v[180:181], v[162:163], v[96:97], v[180:181]
	v_pk_fma_f32 v[182:183], v[160:161], v[96:97], v[182:183]
	v_pk_fma_f32 v[184:185], v[158:159], v[96:97], v[184:185]
	v_pk_fma_f32 v[186:187], v[156:157], v[96:97], v[186:187]
	v_pk_fma_f32 v[188:189], v[154:155], v[96:97], v[188:189]
	v_pk_fma_f32 v[190:191], v[152:153], v[96:97], v[190:191]
	v_pk_fma_f32 v[78:79], v[150:151], v[96:97], v[78:79]
	v_pk_fma_f32 v[80:81], v[148:149], v[96:97], v[80:81]
	v_pk_fma_f32 v[82:83], v[146:147], v[96:97], v[82:83]
	v_pk_fma_f32 v[84:85], v[144:145], v[96:97], v[84:85]
	v_pk_fma_f32 v[86:87], v[142:143], v[96:97], v[86:87]
	v_pk_fma_f32 v[88:89], v[140:141], v[96:97], v[88:89]
	s_waitcnt vmcnt(12)
	v_lshlrev_b32_e32 v98, 16, v226
	v_and_b32_e32 v99, 0xffff0000, v226
	v_pk_fma_f32 v[178:179], v[170:171], v[98:99], v[178:179]
	v_pk_fma_f32 v[180:181], v[168:169], v[98:99], v[180:181]
	v_pk_fma_f32 v[182:183], v[162:163], v[98:99], v[182:183]
	v_pk_fma_f32 v[184:185], v[160:161], v[98:99], v[184:185]
	v_pk_fma_f32 v[186:187], v[158:159], v[98:99], v[186:187]
	v_pk_fma_f32 v[188:189], v[156:157], v[98:99], v[188:189]
	v_pk_fma_f32 v[190:191], v[154:155], v[98:99], v[190:191]
	v_pk_fma_f32 v[78:79], v[152:153], v[98:99], v[78:79]
	v_pk_fma_f32 v[80:81], v[150:151], v[98:99], v[80:81]
	v_pk_fma_f32 v[82:83], v[148:149], v[98:99], v[82:83]
	v_pk_fma_f32 v[84:85], v[146:147], v[98:99], v[84:85]
	v_pk_fma_f32 v[86:87], v[144:145], v[98:99], v[86:87]
	v_pk_fma_f32 v[88:89], v[142:143], v[98:99], v[88:89]
	s_waitcnt vmcnt(11)
	v_lshlrev_b32_e32 v96, 16, v227
	v_and_b32_e32 v97, 0xffff0000, v227
	v_pk_fma_f32 v[180:181], v[170:171], v[96:97], v[180:181]
	v_pk_fma_f32 v[182:183], v[168:169], v[96:97], v[182:183]
	v_pk_fma_f32 v[184:185], v[162:163], v[96:97], v[184:185]
	v_pk_fma_f32 v[186:187], v[160:161], v[96:97], v[186:187]
	v_pk_fma_f32 v[188:189], v[158:159], v[96:97], v[188:189]
	v_pk_fma_f32 v[190:191], v[156:157], v[96:97], v[190:191]
	v_pk_fma_f32 v[78:79], v[154:155], v[96:97], v[78:79]
	v_pk_fma_f32 v[80:81], v[152:153], v[96:97], v[80:81]
	v_pk_fma_f32 v[82:83], v[150:151], v[96:97], v[82:83]
	v_pk_fma_f32 v[84:85], v[148:149], v[96:97], v[84:85]
	v_pk_fma_f32 v[86:87], v[146:147], v[96:97], v[86:87]
	v_pk_fma_f32 v[88:89], v[144:145], v[96:97], v[88:89]
	s_waitcnt vmcnt(10)
; __device__ __forceinline__ f32x2v bf2(unsigned v) { return (f32x2v){bflo(v), bfhi(v)}; }
; __device__ __forceinline__ void mixer_prompt_run(const Args& p, int run, int c2) {
;     ...
;             for (int t = 0; t < 8; ++t) a[t] = cb;
; #pragma unroll
;             for (int i = 0; i < 38; ++i) {
;                 const int ti = t0 + 8 * hh - 30 + i; unsigned v = U32[(rowb + (ti >= 0 ? ti : 0)) * 256 + c2]; v = (ti >= 0) ? v : 0u; const f32x2v x = bf2(v);
; #pragma unroll
;                 for (int t = 0; t < 8; ++t) { const int j = i - t; if (j >= 0 && j <= 30) a[t] = w[j] * x + a[t]; }
;                 if (i == 18) asm volatile("" ::: "memory");
;             }
	v_lshlrev_b32_e32 v98, 16, v228
	v_and_b32_e32 v99, 0xffff0000, v228
	v_pk_fma_f32 v[182:183], v[170:171], v[98:99], v[182:183]
	v_pk_fma_f32 v[184:185], v[168:169], v[98:99], v[184:185]
	v_pk_fma_f32 v[186:187], v[162:163], v[98:99], v[186:187]
	v_pk_fma_f32 v[188:189], v[160:161], v[98:99], v[188:189]
	v_pk_fma_f32 v[190:191], v[158:159], v[98:99], v[190:191]
	v_pk_fma_f32 v[78:79], v[156:157], v[98:99], v[78:79]
	v_pk_fma_f32 v[80:81], v[154:155], v[98:99], v[80:81]
	v_pk_fma_f32 v[82:83], v[152:153], v[98:99], v[82:83]
	v_pk_fma_f32 v[84:85], v[150:151], v[98:99], v[84:85]
	v_pk_fma_f32 v[86:87], v[148:149], v[98:99], v[86:87]
	v_pk_fma_f32 v[88:89], v[146:147], v[98:99], v[88:89]
	s_waitcnt vmcnt(9)
	v_lshlrev_b32_e32 v96, 16, v229
	v_and_b32_e32 v97, 0xffff0000, v229
	v_pk_fma_f32 v[184:185], v[170:171], v[96:97], v[184:185]
	v_pk_fma_f32 v[186:187], v[168:169], v[96:97], v[186:187]
	v_pk_fma_f32 v[188:189], v[162:163], v[96:97], v[188:189]
	v_pk_fma_f32 v[190:191], v[160:161], v[96:97], v[190:191]
	v_pk_fma_f32 v[78:79], v[158:159], v[96:97], v[78:79]
	v_pk_fma_f32 v[80:81], v[156:157], v[96:97], v[80:81]
	v_pk_fma_f32 v[82:83], v[154:155], v[96:97], v[82:83]
	v_pk_fma_f32 v[84:85], v[152:153], v[96:97], v[84:85]
	v_pk_fma_f32 v[86:87], v[150:151], v[96:97], v[86:87]
	v_pk_fma_f32 v[88:89], v[148:149], v[96:97], v[88:89]
	s_waitcnt vmcnt(8)
	v_lshlrev_b32_e32 v98, 16, v230
	v_and_b32_e32 v99, 0xffff0000, v230
	v_pk_fma_f32 v[186:187], v[170:171], v[98:99], v[186:187]
	v_pk_fma_f32 v[188:189], v[168:169], v[98:99], v[188:189]
	v_pk_fma_f32 v[190:191], v[162:163], v[98:99], v[190:191]
	v_pk_fma_f32 v[78:79], v[160:161], v[98:99], v[78:79]
	v_pk_fma_f32 v[80:81], v[158:159], v[98:99], v[80:81]
	v_pk_fma_f32 v[82:83], v[156:157], v[98:99], v[82:83]
	v_pk_fma_f32 v[84:85], v[154:155], v[98:99], v[84:85]
	v_pk_fma_f32 v[86:87], v[152:153], v[98:99], v[86:87]
	v_pk_fma_f32 v[88:89], v[150:151], v[98:99], v[88:89]
	s_waitcnt vmcnt(7)
	v_lshlrev_b32_e32 v96, 16, v231
	v_and_b32_e32 v97, 0xffff0000, v231
	v_pk_fma_f32 v[188:189], v[170:171], v[96:97], v[188:189]
	v_pk_fma_f32 v[190:191], v[168:169], v[96:97], v[190:191]
	v_pk_fma_f32 v[78:79], v[162:163], v[96:97], v[78:79]
	v_pk_fma_f32 v[80:81], v[160:161], v[96:97], v[80:81]
	v_pk_fma_f32 v[82:83], v[158:159], v[96:97], v[82:83]
	v_pk_fma_f32 v[84:85], v[156:157], v[96:97], v[84:85]
	v_pk_fma_f32 v[86:87], v[154:155], v[96:97], v[86:87]
	v_pk_fma_f32 v[88:89], v[152:153], v[96:97], v[88:89]
	s_waitcnt vmcnt(6)
	v_lshlrev_b32_e32 v98, 16, v232
	v_and_b32_e32 v99, 0xffff0000, v232
	v_pk_fma_f32 v[190:191], v[170:171], v[98:99], v[190:191]
	v_pk_fma_f32 v[78:79], v[168:169], v[98:99], v[78:79]
	v_pk_fma_f32 v[80:81], v[162:163], v[98:99], v[80:81]
	v_pk_fma_f32 v[82:83], v[160:161], v[98:99], v[82:83]
	v_pk_fma_f32 v[84:85], v[158:159], v[98:99], v[84:85]
	v_pk_fma_f32 v[86:87], v[156:157], v[98:99], v[86:87]
	v_pk_fma_f32 v[88:89], v[154:155], v[98:99], v[88:89]
	s_waitcnt vmcnt(5)
	v_lshlrev_b32_e32 v96, 16, v233
	v_and_b32_e32 v97, 0xffff0000, v233
	v_pk_fma_f32 v[78:79], v[170:171], v[96:97], v[78:79]
	v_pk_fma_f32 v[80:81], v[168:169], v[96:97], v[80:81]
	v_pk_fma_f32 v[82:83], v[162:163], v[96:97], v[82:83]
	v_pk_fma_f32 v[84:85], v[160:161], v[96:97], v[84:85]
	v_pk_fma_f32 v[86:87], v[158:159], v[96:97], v[86:87]
	v_pk_fma_f32 v[88:89], v[156:157], v[96:97], v[88:89]
	s_waitcnt vmcnt(4)
	v_lshlrev_b32_e32 v98, 16, v234
	v_and_b32_e32 v99, 0xffff0000, v234
	v_pk_fma_f32 v[80:81], v[170:171], v[98:99], v[80:81]
	v_pk_fma_f32 v[82:83], v[168:169], v[98:99], v[82:83]
	v_pk_fma_f32 v[84:85], v[162:163], v[98:99], v[84:85]
	v_pk_fma_f32 v[86:87], v[160:161], v[98:99], v[86:87]
	v_pk_fma_f32 v[88:89], v[158:159], v[98:99], v[88:89]
	s_waitcnt vmcnt(3)
	v_lshlrev_b32_e32 v96, 16, v235
	v_and_b32_e32 v97, 0xffff0000, v235
	v_pk_fma_f32 v[82:83], v[170:171], v[96:97], v[82:83]
	v_pk_fma_f32 v[84:85], v[168:169], v[96:97], v[84:85]
	v_pk_fma_f32 v[86:87], v[162:163], v[96:97], v[86:87]
	v_pk_fma_f32 v[88:89], v[160:161], v[96:97], v[88:89]
	s_waitcnt vmcnt(2)
	v_lshlrev_b32_e32 v98, 16, v236
	v_and_b32_e32 v99, 0xffff0000, v236
	v_pk_fma_f32 v[84:85], v[170:171], v[98:99], v[84:85]
	v_pk_fma_f32 v[86:87], v[168:169], v[98:99], v[86:87]
	v_pk_fma_f32 v[88:89], v[162:163], v[98:99], v[88:89]
	s_waitcnt vmcnt(1)
	v_lshlrev_b32_e32 v96, 16, v237
	v_and_b32_e32 v97, 0xffff0000, v237
	v_pk_fma_f32 v[86:87], v[170:171], v[96:97], v[86:87]
	v_pk_fma_f32 v[88:89], v[168:169], v[96:97], v[88:89]
	s_waitcnt vmcnt(0)
; template <int CTRL> __device__ __forceinline__ float dpp_mov(float v) { return __builtin_bit_cast(float, __builtin_amdgcn_update_dpp(0, __builtin_bit_cast(int, v), CTRL, 0xf, 0xf, true)); }
; __device__ __forceinline__ float half_wave_sum(float v) {
;     v += dpp_mov<0xB1>(v);
;     v += dpp_mov<0x4E>(v);
;     v += dpp_mov<0x141>(v);
;     v += dpp_mov<0x140>(v);
;     v += __shfl_xor(v, 16);
;     return v;
; }
; __device__ __forceinline__ void gn_swish_store(float v0, float v1, f32x2v gg, f32x2v gb, unsigned* dst) {
;     const float mean = half_wave_sum(v0 + v1) * (1.0f / 64.0f); const float d0 = v0 - mean, d1 = v1 - mean;
;     const float rstd = rsqrtf(half_wave_sum(d0 * d0 + d1 * d1) * (1.0f / 64.0f) + LN_EPS);
	v_lshlrev_b32_e32 v98, 16, v238
	v_and_b32_e32 v99, 0xffff0000, v238
	v_pk_fma_f32 v[88:89], v[170:171], v[98:99], v[88:89]
	v_add_f32_e32 v194, v172, v173
	v_add_f32_e32 v198, v174, v175
	v_add_f32_e32 v202, v176, v177
	v_add_f32_e32 v206, v178, v179
	v_add_f32_e32 v210, v180, v181
	v_add_f32_e32 v214, v182, v183
	v_add_f32_e32 v218, v184, v185
	v_add_f32_e32 v222, v186, v187
	v_add_f32_dpp v194, v194, v194 quad_perm:[1,0,3,2] row_mask:0xf bank_mask:0xf bound_ctrl:1
	v_add_f32_dpp v198, v198, v198 quad_perm:[1,0,3,2] row_mask:0xf bank_mask:0xf bound_ctrl:1
	v_add_f32_dpp v202, v202, v202 quad_perm:[1,0,3,2] row_mask:0xf bank_mask:0xf bound_ctrl:1
	v_add_f32_dpp v206, v206, v206 quad_perm:[1,0,3,2] row_mask:0xf bank_mask:0xf bound_ctrl:1
	v_add_f32_dpp v210, v210, v210 quad_perm:[1,0,3,2] row_mask:0xf bank_mask:0xf bound_ctrl:1
	v_add_f32_dpp v214, v214, v214 quad_perm:[1,0,3,2] row_mask:0xf bank_mask:0xf bound_ctrl:1
	v_add_f32_dpp v218, v218, v218 quad_perm:[1,0,3,2] row_mask:0xf bank_mask:0xf bound_ctrl:1
	v_add_f32_dpp v222, v222, v222 quad_perm:[1,0,3,2] row_mask:0xf bank_mask:0xf bound_ctrl:1
	v_add_f32_dpp v194, v194, v194 quad_perm:[2,3,0,1] row_mask:0xf bank_mask:0xf bound_ctrl:1
	v_add_f32_dpp v198, v198, v198 quad_perm:[2,3,0,1] row_mask:0xf bank_mask:0xf bound_ctrl:1
	v_add_f32_dpp v202, v202, v202 quad_perm:[2,3,0,1] row_mask:0xf bank_mask:0xf bound_ctrl:1
	v_add_f32_dpp v206, v206, v206 quad_perm:[2,3,0,1] row_mask:0xf bank_mask:0xf bound_ctrl:1
	v_add_f32_dpp v210, v210, v210 quad_perm:[2,3,0,1] row_mask:0xf bank_mask:0xf bound_ctrl:1
	v_add_f32_dpp v214, v214, v214 quad_perm:[2,3,0,1] row_mask:0xf bank_mask:0xf bound_ctrl:1
	v_add_f32_dpp v218, v218, v218 quad_perm:[2,3,0,1] row_mask:0xf bank_mask:0xf bound_ctrl:1
	v_add_f32_dpp v222, v222, v222 quad_perm:[2,3,0,1] row_mask:0xf bank_mask:0xf bound_ctrl:1
	v_add_f32_dpp v194, v194, v194 row_half_mirror row_mask:0xf bank_mask:0xf bound_ctrl:1
	v_add_f32_dpp v198, v198, v198 row_half_mirror row_mask:0xf bank_mask:0xf bound_ctrl:1
	v_add_f32_dpp v202, v202, v202 row_half_mirror row_mask:0xf bank_mask:0xf bound_ctrl:1
	v_add_f32_dpp v206, v206, v206 row_half_mirror row_mask:0xf bank_mask:0xf bound_ctrl:1
	v_add_f32_dpp v210, v210, v210 row_half_mirror row_mask:0xf bank_mask:0xf bound_ctrl:1
	v_add_f32_dpp v214, v214, v214 row_half_mirror row_mask:0xf bank_mask:0xf bound_ctrl:1
	v_add_f32_dpp v218, v218, v218 row_half_mirror row_mask:0xf bank_mask:0xf bound_ctrl:1
	v_add_f32_dpp v222, v222, v222 row_half_mirror row_mask:0xf bank_mask:0xf bound_ctrl:1
	v_add_f32_dpp v194, v194, v194 row_mirror row_mask:0xf bank_mask:0xf bound_ctrl:1
	v_add_f32_dpp v198, v198, v198 row_mirror row_mask:0xf bank_mask:0xf bound_ctrl:1
	v_add_f32_dpp v202, v202, v202 row_mirror row_mask:0xf bank_mask:0xf bound_ctrl:1
	v_add_f32_dpp v206, v206, v206 row_mirror row_mask:0xf bank_mask:0xf bound_ctrl:1
	v_add_f32_dpp v210, v210, v210 row_mirror row_mask:0xf bank_mask:0xf bound_ctrl:1
	v_add_f32_dpp v214, v214, v214 row_mirror row_mask:0xf bank_mask:0xf bound_ctrl:1
	v_add_f32_dpp v218, v218, v218 row_mirror row_mask:0xf bank_mask:0xf bound_ctrl:1
	v_add_f32_dpp v222, v222, v222 row_mirror row_mask:0xf bank_mask:0xf bound_ctrl:1
	ds_bpermute_b32 v195, v239, v194
	ds_bpermute_b32 v199, v239, v198
	ds_bpermute_b32 v203, v239, v202
	ds_bpermute_b32 v207, v239, v206
	ds_bpermute_b32 v211, v239, v210
	ds_bpermute_b32 v215, v239, v214
	ds_bpermute_b32 v219, v239, v218
	ds_bpermute_b32 v223, v239, v222
	s_waitcnt lgkmcnt(7)
	v_add_f32_e32 v194, v194, v195
	s_waitcnt lgkmcnt(6)
	v_add_f32_e32 v198, v198, v199
	s_waitcnt lgkmcnt(5)
	v_add_f32_e32 v202, v202, v203
	s_waitcnt lgkmcnt(4)
	v_add_f32_e32 v206, v206, v207
	s_waitcnt lgkmcnt(3)
	v_add_f32_e32 v210, v210, v211
	s_waitcnt lgkmcnt(2)
	v_add_f32_e32 v214, v214, v215
	s_waitcnt lgkmcnt(1)
	v_add_f32_e32 v218, v218, v219
	s_waitcnt lgkmcnt(0)
	v_add_f32_e32 v222, v222, v223
	v_pk_fma_f32 v[172:173], v[194:195], s[78:79], v[172:173] op_sel_hi:[0,1,1]
	v_pk_fma_f32 v[174:175], v[198:199], s[78:79], v[174:175] op_sel_hi:[0,1,1]
	v_pk_fma_f32 v[176:177], v[202:203], s[78:79], v[176:177] op_sel_hi:[0,1,1]
	v_pk_fma_f32 v[178:179], v[206:207], s[78:79], v[178:179] op_sel_hi:[0,1,1]
	v_pk_fma_f32 v[180:181], v[210:211], s[78:79], v[180:181] op_sel_hi:[0,1,1]
	v_pk_fma_f32 v[182:183], v[214:215], s[78:79], v[182:183] op_sel_hi:[0,1,1]
	v_pk_fma_f32 v[184:185], v[218:219], s[78:79], v[184:185] op_sel_hi:[0,1,1]
	v_pk_fma_f32 v[186:187], v[222:223], s[78:79], v[186:187] op_sel_hi:[0,1,1]
	v_pk_mul_f32 v[196:197], v[172:173], v[172:173]
	v_pk_mul_f32 v[200:201], v[174:175], v[174:175]
	v_pk_mul_f32 v[204:205], v[176:177], v[176:177]
	v_pk_mul_f32 v[208:209], v[178:179], v[178:179]
	v_pk_mul_f32 v[212:213], v[180:181], v[180:181]
	v_pk_mul_f32 v[216:217], v[182:183], v[182:183]
	v_pk_mul_f32 v[220:221], v[184:185], v[184:185]
	v_pk_mul_f32 v[224:225], v[186:187], v[186:187]
	v_add_f32_e32 v194, v196, v197
	v_add_f32_e32 v198, v200, v201
	v_add_f32_e32 v202, v204, v205
	v_add_f32_e32 v206, v208, v209
	v_add_f32_e32 v210, v212, v213
	v_add_f32_e32 v214, v216, v217
	v_add_f32_e32 v218, v220, v221
	v_add_f32_e32 v222, v224, v225
	v_add_f32_dpp v194, v194, v194 quad_perm:[1,0,3,2] row_mask:0xf bank_mask:0xf bound_ctrl:1
	v_add_f32_dpp v198, v198, v198 quad_perm:[1,0,3,2] row_mask:0xf bank_mask:0xf bound_ctrl:1
	v_add_f32_dpp v202, v202, v202 quad_perm:[1,0,3,2] row_mask:0xf bank_mask:0xf bound_ctrl:1
	v_add_f32_dpp v206, v206, v206 quad_perm:[1,0,3,2] row_mask:0xf bank_mask:0xf bound_ctrl:1
	v_add_f32_dpp v210, v210, v210 quad_perm:[1,0,3,2] row_mask:0xf bank_mask:0xf bound_ctrl:1
; __device__ __forceinline__ unsigned pk2(float lo, float hi) { f32x2v v = {lo, hi}; b16x2v b = __builtin_convertvector(v, b16x2v); return __builtin_bit_cast(unsigned, b); }
; __device__ __forceinline__ float fsigmoid(float x) { return __builtin_amdgcn_rcpf(1.0f + __expf(-x)); }
; template <int CTRL> __device__ __forceinline__ float dpp_mov(float v) { return __builtin_bit_cast(float, __builtin_amdgcn_update_dpp(0, __builtin_bit_cast(int, v), CTRL, 0xf, 0xf, true)); }
; __device__ __forceinline__ float half_wave_sum(float v) {
;     v += dpp_mov<0xB1>(v);
;     v += dpp_mov<0x4E>(v);
;     v += dpp_mov<0x141>(v);
;     v += dpp_mov<0x140>(v);
;     v += __shfl_xor(v, 16);
;     return v;
; }
; __device__ __forceinline__ void gn_swish_store(float v0, float v1, f32x2v gg, f32x2v gb, unsigned* dst) {
;     const float mean = half_wave_sum(v0 + v1) * (1.0f / 64.0f); const float d0 = v0 - mean, d1 = v1 - mean;
;     const float rstd = rsqrtf(half_wave_sum(d0 * d0 + d1 * d1) * (1.0f / 64.0f) + LN_EPS);
;     float y0 = d0 * rstd * gg.x + gb.x, y1 = d1 * rstd * gg.y + gb.y;
;     y0 = y0 * fsigmoid(y0); y1 = y1 * fsigmoid(y1);
;     *dst = pk2(y0, y1);
	v_add_f32_dpp v214, v214, v214 quad_perm:[1,0,3,2] row_mask:0xf bank_mask:0xf bound_ctrl:1
	v_add_f32_dpp v218, v218, v218 quad_perm:[1,0,3,2] row_mask:0xf bank_mask:0xf bound_ctrl:1
	v_add_f32_dpp v222, v222, v222 quad_perm:[1,0,3,2] row_mask:0xf bank_mask:0xf bound_ctrl:1
	v_add_f32_dpp v194, v194, v194 quad_perm:[2,3,0,1] row_mask:0xf bank_mask:0xf bound_ctrl:1
	v_add_f32_dpp v198, v198, v198 quad_perm:[2,3,0,1] row_mask:0xf bank_mask:0xf bound_ctrl:1
	v_add_f32_dpp v202, v202, v202 quad_perm:[2,3,0,1] row_mask:0xf bank_mask:0xf bound_ctrl:1
	v_add_f32_dpp v206, v206, v206 quad_perm:[2,3,0,1] row_mask:0xf bank_mask:0xf bound_ctrl:1
	v_add_f32_dpp v210, v210, v210 quad_perm:[2,3,0,1] row_mask:0xf bank_mask:0xf bound_ctrl:1
	v_add_f32_dpp v214, v214, v214 quad_perm:[2,3,0,1] row_mask:0xf bank_mask:0xf bound_ctrl:1
	v_add_f32_dpp v218, v218, v218 quad_perm:[2,3,0,1] row_mask:0xf bank_mask:0xf bound_ctrl:1
	v_add_f32_dpp v222, v222, v222 quad_perm:[2,3,0,1] row_mask:0xf bank_mask:0xf bound_ctrl:1
	v_add_f32_dpp v194, v194, v194 row_half_mirror row_mask:0xf bank_mask:0xf bound_ctrl:1
	v_add_f32_dpp v198, v198, v198 row_half_mirror row_mask:0xf bank_mask:0xf bound_ctrl:1
	v_add_f32_dpp v202, v202, v202 row_half_mirror row_mask:0xf bank_mask:0xf bound_ctrl:1
	v_add_f32_dpp v206, v206, v206 row_half_mirror row_mask:0xf bank_mask:0xf bound_ctrl:1
	v_add_f32_dpp v210, v210, v210 row_half_mirror row_mask:0xf bank_mask:0xf bound_ctrl:1
	v_add_f32_dpp v214, v214, v214 row_half_mirror row_mask:0xf bank_mask:0xf bound_ctrl:1
	v_add_f32_dpp v218, v218, v218 row_half_mirror row_mask:0xf bank_mask:0xf bound_ctrl:1
	v_add_f32_dpp v222, v222, v222 row_half_mirror row_mask:0xf bank_mask:0xf bound_ctrl:1
	v_add_f32_dpp v194, v194, v194 row_mirror row_mask:0xf bank_mask:0xf bound_ctrl:1
	v_add_f32_dpp v198, v198, v198 row_mirror row_mask:0xf bank_mask:0xf bound_ctrl:1
	v_add_f32_dpp v202, v202, v202 row_mirror row_mask:0xf bank_mask:0xf bound_ctrl:1
	v_add_f32_dpp v206, v206, v206 row_mirror row_mask:0xf bank_mask:0xf bound_ctrl:1
	v_add_f32_dpp v210, v210, v210 row_mirror row_mask:0xf bank_mask:0xf bound_ctrl:1
	v_add_f32_dpp v214, v214, v214 row_mirror row_mask:0xf bank_mask:0xf bound_ctrl:1
	v_add_f32_dpp v218, v218, v218 row_mirror row_mask:0xf bank_mask:0xf bound_ctrl:1
	v_add_f32_dpp v222, v222, v222 row_mirror row_mask:0xf bank_mask:0xf bound_ctrl:1
	ds_bpermute_b32 v195, v239, v194
	ds_bpermute_b32 v199, v239, v198
	ds_bpermute_b32 v203, v239, v202
	ds_bpermute_b32 v207, v239, v206
	ds_bpermute_b32 v211, v239, v210
	ds_bpermute_b32 v215, v239, v214
	ds_bpermute_b32 v219, v239, v218
	ds_bpermute_b32 v223, v239, v222
	s_waitcnt lgkmcnt(7)
	v_add_f32_e32 v194, v194, v195
	s_waitcnt lgkmcnt(6)
	v_add_f32_e32 v198, v198, v199
	s_waitcnt lgkmcnt(5)
	v_add_f32_e32 v202, v202, v203
	s_waitcnt lgkmcnt(4)
	v_add_f32_e32 v206, v206, v207
	s_waitcnt lgkmcnt(3)
	v_add_f32_e32 v210, v210, v211
	s_waitcnt lgkmcnt(2)
	v_add_f32_e32 v214, v214, v215
	s_waitcnt lgkmcnt(1)
	v_add_f32_e32 v218, v218, v219
	s_waitcnt lgkmcnt(0)
	v_add_f32_e32 v222, v222, v223
	v_fma_f32 v194, v194, s48, v241
	v_fma_f32 v198, v198, s48, v241
	v_fma_f32 v202, v202, s48, v241
	v_fma_f32 v206, v206, s48, v241
	v_fma_f32 v210, v210, s48, v241
	v_fma_f32 v214, v214, s48, v241
	v_fma_f32 v218, v218, s48, v241
	v_fma_f32 v222, v222, s48, v241
	v_rsq_f32_e32 v194, v194
	v_rsq_f32_e32 v198, v198
	v_rsq_f32_e32 v202, v202
	v_rsq_f32_e32 v206, v206
	v_rsq_f32_e32 v210, v210
	v_rsq_f32_e32 v214, v214
	v_rsq_f32_e32 v218, v218
	v_rsq_f32_e32 v222, v222
	v_pk_mul_f32 v[172:173], v[172:173], v[194:195] op_sel_hi:[1,0]
	v_pk_mul_f32 v[174:175], v[174:175], v[198:199] op_sel_hi:[1,0]
	v_pk_mul_f32 v[176:177], v[176:177], v[202:203] op_sel_hi:[1,0]
	v_pk_mul_f32 v[178:179], v[178:179], v[206:207] op_sel_hi:[1,0]
	v_pk_mul_f32 v[180:181], v[180:181], v[210:211] op_sel_hi:[1,0]
	v_pk_mul_f32 v[182:183], v[182:183], v[214:215] op_sel_hi:[1,0]
	v_pk_mul_f32 v[184:185], v[184:185], v[218:219] op_sel_hi:[1,0]
	v_pk_mul_f32 v[186:187], v[186:187], v[222:223] op_sel_hi:[1,0]
	v_pk_fma_f32 v[172:173], v[172:173], v[92:93], v[94:95]
	v_pk_fma_f32 v[174:175], v[174:175], v[92:93], v[94:95]
	v_pk_fma_f32 v[176:177], v[176:177], v[92:93], v[94:95]
	v_pk_fma_f32 v[178:179], v[178:179], v[92:93], v[94:95]
	v_pk_fma_f32 v[180:181], v[180:181], v[92:93], v[94:95]
	v_pk_fma_f32 v[182:183], v[182:183], v[92:93], v[94:95]
	v_pk_fma_f32 v[184:185], v[184:185], v[92:93], v[94:95]
	v_pk_fma_f32 v[186:187], v[186:187], v[92:93], v[94:95]
	v_pk_mul_f32 v[196:197], v[172:173], s[80:81]
	v_pk_mul_f32 v[200:201], v[174:175], s[80:81]
	v_pk_mul_f32 v[204:205], v[176:177], s[80:81]
	v_pk_mul_f32 v[208:209], v[178:179], s[80:81]
	v_pk_mul_f32 v[212:213], v[180:181], s[80:81]
	v_pk_mul_f32 v[216:217], v[182:183], s[80:81]
	v_pk_mul_f32 v[220:221], v[184:185], s[80:81]
	v_pk_mul_f32 v[224:225], v[186:187], s[80:81]
	v_exp_f32_e32 v196, v196
	v_exp_f32_e32 v197, v197
	v_exp_f32_e32 v200, v200
	v_exp_f32_e32 v201, v201
	v_exp_f32_e32 v204, v204
	v_exp_f32_e32 v205, v205
	v_exp_f32_e32 v208, v208
	v_exp_f32_e32 v209, v209
	v_exp_f32_e32 v212, v212
	v_exp_f32_e32 v213, v213
	v_exp_f32_e32 v216, v216
	v_exp_f32_e32 v217, v217
	v_exp_f32_e32 v220, v220
	v_exp_f32_e32 v221, v221
	v_exp_f32_e32 v224, v224
	v_exp_f32_e32 v225, v225
	v_pk_add_f32 v[196:197], v[196:197], s[86:87]
	v_pk_add_f32 v[200:201], v[200:201], s[86:87]
	v_pk_add_f32 v[204:205], v[204:205], s[86:87]
	v_pk_add_f32 v[208:209], v[208:209], s[86:87]
	v_pk_add_f32 v[212:213], v[212:213], s[86:87]
	v_pk_add_f32 v[216:217], v[216:217], s[86:87]
	v_pk_add_f32 v[220:221], v[220:221], s[86:87]
; __device__ __forceinline__ unsigned pk2(float lo, float hi) { f32x2v v = {lo, hi}; b16x2v b = __builtin_convertvector(v, b16x2v); return __builtin_bit_cast(unsigned, b); }
; __device__ __forceinline__ float fsigmoid(float x) { return __builtin_amdgcn_rcpf(1.0f + __expf(-x)); }
; __device__ __forceinline__ void gn_swish_store(float v0, float v1, f32x2v gg, f32x2v gb, unsigned* dst) {
;     const float mean = half_wave_sum(v0 + v1) * (1.0f / 64.0f); const float d0 = v0 - mean, d1 = v1 - mean;
;     const float rstd = rsqrtf(half_wave_sum(d0 * d0 + d1 * d1) * (1.0f / 64.0f) + LN_EPS);
;     float y0 = d0 * rstd * gg.x + gb.x, y1 = d1 * rstd * gg.y + gb.y;
;     y0 = y0 * fsigmoid(y0); y1 = y1 * fsigmoid(y1);
;     *dst = pk2(y0, y1);
; }
	v_pk_add_f32 v[224:225], v[224:225], s[86:87]
	v_rcp_f32_e32 v196, v196
	v_rcp_f32_e32 v197, v197
	v_rcp_f32_e32 v200, v200
	v_rcp_f32_e32 v201, v201
	v_rcp_f32_e32 v204, v204
	v_rcp_f32_e32 v205, v205
	v_rcp_f32_e32 v208, v208
	v_rcp_f32_e32 v209, v209
	v_rcp_f32_e32 v212, v212
	v_rcp_f32_e32 v213, v213
	v_rcp_f32_e32 v216, v216
	v_rcp_f32_e32 v217, v217
	v_rcp_f32_e32 v220, v220
	v_rcp_f32_e32 v221, v221
	v_rcp_f32_e32 v224, v224
	v_rcp_f32_e32 v225, v225
	v_pk_mul_f32 v[172:173], v[172:173], v[196:197]
	v_pk_mul_f32 v[174:175], v[174:175], v[200:201]
	v_pk_mul_f32 v[176:177], v[176:177], v[204:205]
	v_pk_mul_f32 v[178:179], v[178:179], v[208:209]
	v_pk_mul_f32 v[180:181], v[180:181], v[212:213]
	v_pk_mul_f32 v[182:183], v[182:183], v[216:217]
	v_pk_mul_f32 v[184:185], v[184:185], v[220:221]
	v_pk_mul_f32 v[186:187], v[186:187], v[224:225]
	v_cvt_pk_bf16_f32 v194, v172, v173
	v_cvt_pk_bf16_f32 v198, v174, v175
	v_cvt_pk_bf16_f32 v202, v176, v177
	v_cvt_pk_bf16_f32 v206, v178, v179
	v_cvt_pk_bf16_f32 v210, v180, v181
	v_cvt_pk_bf16_f32 v214, v182, v183
	v_cvt_pk_bf16_f32 v218, v184, v185
	v_cvt_pk_bf16_f32 v222, v186, v187
	global_store_dword v105, v194, s[70:71] offset:-4096
	global_store_dword v105, v198, s[70:71] offset:-2048
	global_store_dword v105, v202, s[70:71] offset:0
	global_store_dword v105, v206, s[70:71] offset:2048
	s_add_u32 s70, s70, 0x2000
	s_addc_u32 s71, s71, 0
	global_store_dword v105, v210, s[70:71] offset:-4096
	global_store_dword v105, v214, s[70:71] offset:-2048
	global_store_dword v105, v218, s[70:71] offset:0
	global_store_dword v105, v222, s[70:71] offset:2048
	v_add_f32_e32 v194, v188, v189
	v_add_f32_e32 v198, v190, v191
	v_add_f32_e32 v202, v78, v79
	v_add_f32_e32 v206, v80, v81
	v_add_f32_e32 v210, v82, v83
	v_add_f32_e32 v214, v84, v85
	v_add_f32_e32 v218, v86, v87
	v_add_f32_e32 v222, v88, v89
	v_add_f32_dpp v194, v194, v194 quad_perm:[1,0,3,2] row_mask:0xf bank_mask:0xf bound_ctrl:1
	v_add_f32_dpp v198, v198, v198 quad_perm:[1,0,3,2] row_mask:0xf bank_mask:0xf bound_ctrl:1
	v_add_f32_dpp v202, v202, v202 quad_perm:[1,0,3,2] row_mask:0xf bank_mask:0xf bound_ctrl:1
	v_add_f32_dpp v206, v206, v206 quad_perm:[1,0,3,2] row_mask:0xf bank_mask:0xf bound_ctrl:1
	v_add_f32_dpp v210, v210, v210 quad_perm:[1,0,3,2] row_mask:0xf bank_mask:0xf bound_ctrl:1
	v_add_f32_dpp v214, v214, v214 quad_perm:[1,0,3,2] row_mask:0xf bank_mask:0xf bound_ctrl:1
	v_add_f32_dpp v218, v218, v218 quad_perm:[1,0,3,2] row_mask:0xf bank_mask:0xf bound_ctrl:1
	v_add_f32_dpp v222, v222, v222 quad_perm:[1,0,3,2] row_mask:0xf bank_mask:0xf bound_ctrl:1
	v_add_f32_dpp v194, v194, v194 quad_perm:[2,3,0,1] row_mask:0xf bank_mask:0xf bound_ctrl:1
	v_add_f32_dpp v198, v198, v198 quad_perm:[2,3,0,1] row_mask:0xf bank_mask:0xf bound_ctrl:1
	v_add_f32_dpp v202, v202, v202 quad_perm:[2,3,0,1] row_mask:0xf bank_mask:0xf bound_ctrl:1
	v_add_f32_dpp v206, v206, v206 quad_perm:[2,3,0,1] row_mask:0xf bank_mask:0xf bound_ctrl:1
	v_add_f32_dpp v210, v210, v210 quad_perm:[2,3,0,1] row_mask:0xf bank_mask:0xf bound_ctrl:1
	v_add_f32_dpp v214, v214, v214 quad_perm:[2,3,0,1] row_mask:0xf bank_mask:0xf bound_ctrl:1
	v_add_f32_dpp v218, v218, v218 quad_perm:[2,3,0,1] row_mask:0xf bank_mask:0xf bound_ctrl:1
	v_add_f32_dpp v222, v222, v222 quad_perm:[2,3,0,1] row_mask:0xf bank_mask:0xf bound_ctrl:1
	v_add_f32_dpp v194, v194, v194 row_half_mirror row_mask:0xf bank_mask:0xf bound_ctrl:1
	v_add_f32_dpp v198, v198, v198 row_half_mirror row_mask:0xf bank_mask:0xf bound_ctrl:1
	v_add_f32_dpp v202, v202, v202 row_half_mirror row_mask:0xf bank_mask:0xf bound_ctrl:1
	v_add_f32_dpp v206, v206, v206 row_half_mirror row_mask:0xf bank_mask:0xf bound_ctrl:1
	v_add_f32_dpp v210, v210, v210 row_half_mirror row_mask:0xf bank_mask:0xf bound_ctrl:1
	v_add_f32_dpp v214, v214, v214 row_half_mirror row_mask:0xf bank_mask:0xf bound_ctrl:1
	v_add_f32_dpp v218, v218, v218 row_half_mirror row_mask:0xf bank_mask:0xf bound_ctrl:1
	v_add_f32_dpp v222, v222, v222 row_half_mirror row_mask:0xf bank_mask:0xf bound_ctrl:1
	v_add_f32_dpp v194, v194, v194 row_mirror row_mask:0xf bank_mask:0xf bound_ctrl:1
	v_add_f32_dpp v198, v198, v198 row_mirror row_mask:0xf bank_mask:0xf bound_ctrl:1
	v_add_f32_dpp v202, v202, v202 row_mirror row_mask:0xf bank_mask:0xf bound_ctrl:1
	v_add_f32_dpp v206, v206, v206 row_mirror row_mask:0xf bank_mask:0xf bound_ctrl:1
	v_add_f32_dpp v210, v210, v210 row_mirror row_mask:0xf bank_mask:0xf bound_ctrl:1
	v_add_f32_dpp v214, v214, v214 row_mirror row_mask:0xf bank_mask:0xf bound_ctrl:1
	v_add_f32_dpp v218, v218, v218 row_mirror row_mask:0xf bank_mask:0xf bound_ctrl:1
	v_add_f32_dpp v222, v222, v222 row_mirror row_mask:0xf bank_mask:0xf bound_ctrl:1
	ds_bpermute_b32 v195, v239, v194
	ds_bpermute_b32 v199, v239, v198
	ds_bpermute_b32 v203, v239, v202
	ds_bpermute_b32 v207, v239, v206
	ds_bpermute_b32 v211, v239, v210
	ds_bpermute_b32 v215, v239, v214
	ds_bpermute_b32 v219, v239, v218
	ds_bpermute_b32 v223, v239, v222
	s_waitcnt lgkmcnt(7)
	v_add_f32_e32 v194, v194, v195
	s_waitcnt lgkmcnt(6)
	v_add_f32_e32 v198, v198, v199
	s_waitcnt lgkmcnt(5)
	v_add_f32_e32 v202, v202, v203
	s_waitcnt lgkmcnt(4)
	v_add_f32_e32 v206, v206, v207
	s_waitcnt lgkmcnt(3)
	v_add_f32_e32 v210, v210, v211
	s_waitcnt lgkmcnt(2)
	v_add_f32_e32 v214, v214, v215
	s_waitcnt lgkmcnt(1)
	v_add_f32_e32 v218, v218, v219
	s_waitcnt lgkmcnt(0)
; template <int CTRL> __device__ __forceinline__ float dpp_mov(float v) { return __builtin_bit_cast(float, __builtin_amdgcn_update_dpp(0, __builtin_bit_cast(int, v), CTRL, 0xf, 0xf, true)); }
; __device__ __forceinline__ float half_wave_sum(float v) {
;     v += dpp_mov<0xB1>(v);
;     v += dpp_mov<0x4E>(v);
;     v += dpp_mov<0x141>(v);
;     v += dpp_mov<0x140>(v);
;     v += __shfl_xor(v, 16);
;     return v;
; }
; __device__ __forceinline__ void gn_swish_store(float v0, float v1, f32x2v gg, f32x2v gb, unsigned* dst) {
;     const float mean = half_wave_sum(v0 + v1) * (1.0f / 64.0f); const float d0 = v0 - mean, d1 = v1 - mean;
;     const float rstd = rsqrtf(half_wave_sum(d0 * d0 + d1 * d1) * (1.0f / 64.0f) + LN_EPS);
	v_add_f32_e32 v222, v222, v223
	v_pk_fma_f32 v[188:189], v[194:195], s[78:79], v[188:189] op_sel_hi:[0,1,1]
	v_pk_fma_f32 v[190:191], v[198:199], s[78:79], v[190:191] op_sel_hi:[0,1,1]
	v_pk_fma_f32 v[78:79], v[202:203], s[78:79], v[78:79] op_sel_hi:[0,1,1]
	v_pk_fma_f32 v[80:81], v[206:207], s[78:79], v[80:81] op_sel_hi:[0,1,1]
	v_pk_fma_f32 v[82:83], v[210:211], s[78:79], v[82:83] op_sel_hi:[0,1,1]
	v_pk_fma_f32 v[84:85], v[214:215], s[78:79], v[84:85] op_sel_hi:[0,1,1]
	v_pk_fma_f32 v[86:87], v[218:219], s[78:79], v[86:87] op_sel_hi:[0,1,1]
	v_pk_fma_f32 v[88:89], v[222:223], s[78:79], v[88:89] op_sel_hi:[0,1,1]
	v_pk_mul_f32 v[196:197], v[188:189], v[188:189]
	v_pk_mul_f32 v[200:201], v[190:191], v[190:191]
	v_pk_mul_f32 v[204:205], v[78:79], v[78:79]
	v_pk_mul_f32 v[208:209], v[80:81], v[80:81]
	v_pk_mul_f32 v[212:213], v[82:83], v[82:83]
	v_pk_mul_f32 v[216:217], v[84:85], v[84:85]
	v_pk_mul_f32 v[220:221], v[86:87], v[86:87]
	v_pk_mul_f32 v[224:225], v[88:89], v[88:89]
	v_add_f32_e32 v194, v196, v197
	v_add_f32_e32 v198, v200, v201
	v_add_f32_e32 v202, v204, v205
	v_add_f32_e32 v206, v208, v209
	v_add_f32_e32 v210, v212, v213
	v_add_f32_e32 v214, v216, v217
	v_add_f32_e32 v218, v220, v221
	v_add_f32_e32 v222, v224, v225
	v_add_f32_dpp v194, v194, v194 quad_perm:[1,0,3,2] row_mask:0xf bank_mask:0xf bound_ctrl:1
	v_add_f32_dpp v198, v198, v198 quad_perm:[1,0,3,2] row_mask:0xf bank_mask:0xf bound_ctrl:1
	v_add_f32_dpp v202, v202, v202 quad_perm:[1,0,3,2] row_mask:0xf bank_mask:0xf bound_ctrl:1
	v_add_f32_dpp v206, v206, v206 quad_perm:[1,0,3,2] row_mask:0xf bank_mask:0xf bound_ctrl:1
	v_add_f32_dpp v210, v210, v210 quad_perm:[1,0,3,2] row_mask:0xf bank_mask:0xf bound_ctrl:1
	v_add_f32_dpp v214, v214, v214 quad_perm:[1,0,3,2] row_mask:0xf bank_mask:0xf bound_ctrl:1
	v_add_f32_dpp v218, v218, v218 quad_perm:[1,0,3,2] row_mask:0xf bank_mask:0xf bound_ctrl:1
	v_add_f32_dpp v222, v222, v222 quad_perm:[1,0,3,2] row_mask:0xf bank_mask:0xf bound_ctrl:1
	v_add_f32_dpp v194, v194, v194 quad_perm:[2,3,0,1] row_mask:0xf bank_mask:0xf bound_ctrl:1
	v_add_f32_dpp v198, v198, v198 quad_perm:[2,3,0,1] row_mask:0xf bank_mask:0xf bound_ctrl:1
	v_add_f32_dpp v202, v202, v202 quad_perm:[2,3,0,1] row_mask:0xf bank_mask:0xf bound_ctrl:1
	v_add_f32_dpp v206, v206, v206 quad_perm:[2,3,0,1] row_mask:0xf bank_mask:0xf bound_ctrl:1
	v_add_f32_dpp v210, v210, v210 quad_perm:[2,3,0,1] row_mask:0xf bank_mask:0xf bound_ctrl:1
	v_add_f32_dpp v214, v214, v214 quad_perm:[2,3,0,1] row_mask:0xf bank_mask:0xf bound_ctrl:1
	v_add_f32_dpp v218, v218, v218 quad_perm:[2,3,0,1] row_mask:0xf bank_mask:0xf bound_ctrl:1
	v_add_f32_dpp v222, v222, v222 quad_perm:[2,3,0,1] row_mask:0xf bank_mask:0xf bound_ctrl:1
	v_add_f32_dpp v194, v194, v194 row_half_mirror row_mask:0xf bank_mask:0xf bound_ctrl:1
	v_add_f32_dpp v198, v198, v198 row_half_mirror row_mask:0xf bank_mask:0xf bound_ctrl:1
	v_add_f32_dpp v202, v202, v202 row_half_mirror row_mask:0xf bank_mask:0xf bound_ctrl:1
	v_add_f32_dpp v206, v206, v206 row_half_mirror row_mask:0xf bank_mask:0xf bound_ctrl:1
	v_add_f32_dpp v210, v210, v210 row_half_mirror row_mask:0xf bank_mask:0xf bound_ctrl:1
	v_add_f32_dpp v214, v214, v214 row_half_mirror row_mask:0xf bank_mask:0xf bound_ctrl:1
	v_add_f32_dpp v218, v218, v218 row_half_mirror row_mask:0xf bank_mask:0xf bound_ctrl:1
	v_add_f32_dpp v222, v222, v222 row_half_mirror row_mask:0xf bank_mask:0xf bound_ctrl:1
	v_add_f32_dpp v194, v194, v194 row_mirror row_mask:0xf bank_mask:0xf bound_ctrl:1
	v_add_f32_dpp v198, v198, v198 row_mirror row_mask:0xf bank_mask:0xf bound_ctrl:1
	v_add_f32_dpp v202, v202, v202 row_mirror row_mask:0xf bank_mask:0xf bound_ctrl:1
	v_add_f32_dpp v206, v206, v206 row_mirror row_mask:0xf bank_mask:0xf bound_ctrl:1
	v_add_f32_dpp v210, v210, v210 row_mirror row_mask:0xf bank_mask:0xf bound_ctrl:1
	v_add_f32_dpp v214, v214, v214 row_mirror row_mask:0xf bank_mask:0xf bound_ctrl:1
	v_add_f32_dpp v218, v218, v218 row_mirror row_mask:0xf bank_mask:0xf bound_ctrl:1
	v_add_f32_dpp v222, v222, v222 row_mirror row_mask:0xf bank_mask:0xf bound_ctrl:1
	ds_bpermute_b32 v195, v239, v194
	ds_bpermute_b32 v199, v239, v198
	ds_bpermute_b32 v203, v239, v202
	ds_bpermute_b32 v207, v239, v206
	ds_bpermute_b32 v211, v239, v210
	ds_bpermute_b32 v215, v239, v214
	ds_bpermute_b32 v219, v239, v218
	ds_bpermute_b32 v223, v239, v222
	s_waitcnt lgkmcnt(7)
	v_add_f32_e32 v194, v194, v195
	s_waitcnt lgkmcnt(6)
	v_add_f32_e32 v198, v198, v199
	s_waitcnt lgkmcnt(5)
; __device__ __forceinline__ unsigned pk2(float lo, float hi) { f32x2v v = {lo, hi}; b16x2v b = __builtin_convertvector(v, b16x2v); return __builtin_bit_cast(unsigned, b); }
; __device__ __forceinline__ float fsigmoid(float x) { return __builtin_amdgcn_rcpf(1.0f + __expf(-x)); }
; __device__ __forceinline__ void gn_swish_store(float v0, float v1, f32x2v gg, f32x2v gb, unsigned* dst) {
;     const float mean = half_wave_sum(v0 + v1) * (1.0f / 64.0f); const float d0 = v0 - mean, d1 = v1 - mean;
;     const float rstd = rsqrtf(half_wave_sum(d0 * d0 + d1 * d1) * (1.0f / 64.0f) + LN_EPS);
;     float y0 = d0 * rstd * gg.x + gb.x, y1 = d1 * rstd * gg.y + gb.y;
;     y0 = y0 * fsigmoid(y0); y1 = y1 * fsigmoid(y1);
;     *dst = pk2(y0, y1);
; }
	v_add_f32_e32 v202, v202, v203
	s_waitcnt lgkmcnt(4)
	v_add_f32_e32 v206, v206, v207
	s_waitcnt lgkmcnt(3)
	v_add_f32_e32 v210, v210, v211
	s_waitcnt lgkmcnt(2)
	v_add_f32_e32 v214, v214, v215
	s_waitcnt lgkmcnt(1)
	v_add_f32_e32 v218, v218, v219
	s_waitcnt lgkmcnt(0)
	v_add_f32_e32 v222, v222, v223
	v_fma_f32 v194, v194, s48, v241
	v_fma_f32 v198, v198, s48, v241
	v_fma_f32 v202, v202, s48, v241
	v_fma_f32 v206, v206, s48, v241
	v_fma_f32 v210, v210, s48, v241
	v_fma_f32 v214, v214, s48, v241
	v_fma_f32 v218, v218, s48, v241
	v_fma_f32 v222, v222, s48, v241
	v_rsq_f32_e32 v194, v194
	v_rsq_f32_e32 v198, v198
	v_rsq_f32_e32 v202, v202
	v_rsq_f32_e32 v206, v206
	v_rsq_f32_e32 v210, v210
	v_rsq_f32_e32 v214, v214
	v_rsq_f32_e32 v218, v218
	v_rsq_f32_e32 v222, v222
	v_pk_mul_f32 v[188:189], v[188:189], v[194:195] op_sel_hi:[1,0]
	v_pk_mul_f32 v[190:191], v[190:191], v[198:199] op_sel_hi:[1,0]
	v_pk_mul_f32 v[78:79], v[78:79], v[202:203] op_sel_hi:[1,0]
	v_pk_mul_f32 v[80:81], v[80:81], v[206:207] op_sel_hi:[1,0]
	v_pk_mul_f32 v[82:83], v[82:83], v[210:211] op_sel_hi:[1,0]
	v_pk_mul_f32 v[84:85], v[84:85], v[214:215] op_sel_hi:[1,0]
	v_pk_mul_f32 v[86:87], v[86:87], v[218:219] op_sel_hi:[1,0]
	v_pk_mul_f32 v[88:89], v[88:89], v[222:223] op_sel_hi:[1,0]
	v_pk_fma_f32 v[188:189], v[188:189], v[92:93], v[94:95]
	v_pk_fma_f32 v[190:191], v[190:191], v[92:93], v[94:95]
	v_pk_fma_f32 v[78:79], v[78:79], v[92:93], v[94:95]
	v_pk_fma_f32 v[80:81], v[80:81], v[92:93], v[94:95]
	v_pk_fma_f32 v[82:83], v[82:83], v[92:93], v[94:95]
	v_pk_fma_f32 v[84:85], v[84:85], v[92:93], v[94:95]
	v_pk_fma_f32 v[86:87], v[86:87], v[92:93], v[94:95]
	v_pk_fma_f32 v[88:89], v[88:89], v[92:93], v[94:95]
	v_pk_mul_f32 v[196:197], v[188:189], s[80:81]
	v_pk_mul_f32 v[200:201], v[190:191], s[80:81]
	v_pk_mul_f32 v[204:205], v[78:79], s[80:81]
	v_pk_mul_f32 v[208:209], v[80:81], s[80:81]
	v_pk_mul_f32 v[212:213], v[82:83], s[80:81]
	v_pk_mul_f32 v[216:217], v[84:85], s[80:81]
	v_pk_mul_f32 v[220:221], v[86:87], s[80:81]
	v_pk_mul_f32 v[224:225], v[88:89], s[80:81]
	v_exp_f32_e32 v196, v196
	v_exp_f32_e32 v197, v197
	v_exp_f32_e32 v200, v200
	v_exp_f32_e32 v201, v201
	v_exp_f32_e32 v204, v204
	v_exp_f32_e32 v205, v205
	v_exp_f32_e32 v208, v208
	v_exp_f32_e32 v209, v209
	v_exp_f32_e32 v212, v212
	v_exp_f32_e32 v213, v213
	v_exp_f32_e32 v216, v216
	v_exp_f32_e32 v217, v217
	v_exp_f32_e32 v220, v220
	v_exp_f32_e32 v221, v221
	v_exp_f32_e32 v224, v224
	v_exp_f32_e32 v225, v225
	v_pk_add_f32 v[196:197], v[196:197], s[86:87]
	v_pk_add_f32 v[200:201], v[200:201], s[86:87]
	v_pk_add_f32 v[204:205], v[204:205], s[86:87]
	v_pk_add_f32 v[208:209], v[208:209], s[86:87]
	v_pk_add_f32 v[212:213], v[212:213], s[86:87]
	v_pk_add_f32 v[216:217], v[216:217], s[86:87]
	v_pk_add_f32 v[220:221], v[220:221], s[86:87]
	v_pk_add_f32 v[224:225], v[224:225], s[86:87]
	v_rcp_f32_e32 v196, v196
	v_rcp_f32_e32 v197, v197
	v_rcp_f32_e32 v200, v200
	v_rcp_f32_e32 v201, v201
	v_rcp_f32_e32 v204, v204
	v_rcp_f32_e32 v205, v205
	v_rcp_f32_e32 v208, v208
	v_rcp_f32_e32 v209, v209
	v_rcp_f32_e32 v212, v212
	v_rcp_f32_e32 v213, v213
	v_rcp_f32_e32 v216, v216
	v_rcp_f32_e32 v217, v217
	v_rcp_f32_e32 v220, v220
	v_rcp_f32_e32 v221, v221
	v_rcp_f32_e32 v224, v224
	v_rcp_f32_e32 v225, v225
	v_pk_mul_f32 v[188:189], v[188:189], v[196:197]
	v_pk_mul_f32 v[190:191], v[190:191], v[200:201]
	v_pk_mul_f32 v[78:79], v[78:79], v[204:205]
	v_pk_mul_f32 v[80:81], v[80:81], v[208:209]
	v_pk_mul_f32 v[82:83], v[82:83], v[212:213]
	v_pk_mul_f32 v[84:85], v[84:85], v[216:217]
	v_pk_mul_f32 v[86:87], v[86:87], v[220:221]
	v_pk_mul_f32 v[88:89], v[88:89], v[224:225]
	v_cvt_pk_bf16_f32 v194, v188, v189
	v_cvt_pk_bf16_f32 v198, v190, v191
	v_cvt_pk_bf16_f32 v202, v78, v79
	v_cvt_pk_bf16_f32 v206, v80, v81
	v_cvt_pk_bf16_f32 v210, v82, v83
	v_cvt_pk_bf16_f32 v214, v84, v85
	v_cvt_pk_bf16_f32 v218, v86, v87
	v_cvt_pk_bf16_f32 v222, v88, v89
	s_add_u32 s70, s70, 0x2000
	s_addc_u32 s71, s71, 0
	global_store_dword v105, v194, s[70:71] offset:-4096
	global_store_dword v105, v198, s[70:71] offset:-2048
	global_store_dword v105, v202, s[70:71] offset:0
	global_store_dword v105, v206, s[70:71] offset:2048
	s_add_u32 s70, s70, 0x2000
	s_addc_u32 s71, s71, 0
	global_store_dword v105, v210, s[70:71] offset:-4096
	global_store_dword v105, v214, s[70:71] offset:-2048
	global_store_dword v105, v218, s[70:71] offset:0
	global_store_dword v105, v222, s[70:71] offset:2048
	s_branch .Lmx_done
